# nt on GEMM1 stores + nt on up-GEMM gate loads + nt on out-GEMM base loads (l>0 path)
# baseline (speedup 1.0000x reference)
; __device__ __forceinline__ float bf_lo(unsigned w) { return __uint_as_float(w << 16); }
; __device__ __forceinline__ float bf_hi(unsigned w) { return __uint_as_float(w & 0xffff0000u); }
; #define RT(a, b) ((b) * __builtin_amdgcn_rcpf(a))
;     __device__ __forceinline__ void hook(f32x4 (&acc)[2][2][4][2], const Unit& u, int which, int wr, int wc, int fr, int fq) const {
;     ...
;                     for (int bj = 0; bj < 2; ++bj) { const unsigned off = off0 + (unsigned)(((ai * 4 + m) * 2 + bj) * 1024);
;                         gnv[m][bj] = *(const u32x4*)(gn_b + off); gdv[m][bj] = *(const u32x4*)(gd_b + off); }
; #pragma unroll
;                 for (int m = 0; m < 4; ++m)
; #pragma unroll
;                     for (int bj = 0; bj < 2; ++bj) { const u32x4 gn = gnv[m][bj], gd = gdv[m][bj];
;     ...
;                         f32x4 r0, r1;
;                         r0[0] = RT(bf_lo(gn.x), bf_lo(gd.x)); r0[1] = RT(bf_hi(gn.x), bf_hi(gd.x)); r0[2] = RT(bf_lo(gn.y), bf_lo(gd.y)); r0[3] = RT(bf_hi(gn.y), bf_hi(gd.y));
;                         r1[0] = RT(bf_lo(gn.z), bf_lo(gd.z)); r1[1] = RT(bf_hi(gn.z), bf_hi(gd.z)); r1[2] = RT(bf_lo(gn.w), bf_lo(gd.w)); r1[3] = RT(bf_hi(gn.w), bf_hi(gd.w));
;     ...
;                         acc[ai][bj][m][0] *= r0; acc[ai][bj][m][1] *= r1; }
.LBB0_52:
	s_andn2_b64 vcc, exec, s[66:67]
	s_cbranch_vccnz .LBB0_54
	v_mov_b32_e32 v96, v212
	s_nop 0
	v_readfirstlane_b32 s66, v96
	s_ashr_i32 s66, s66, 6
	s_cmp_eq_u32 s86, 4
	s_cselect_b32 s67, 0, 0x1000
	s_add_i32 s66, s66, s36
	s_add_i32 s67, s67, s31
	s_add_i32 s68, s67, s66
	s_ashr_i32 s69, s68, 31
	s_lshl_b64 s[66:67], s[68:69], 14
	s_add_u32 s66, s33, s66
	s_addc_u32 s67, s37, s67
	s_addk_i32 s68, 0x1000
	s_ashr_i32 s69, s68, 31
	v_lshlrev_b32_e32 v96, 4, v96
	s_lshl_b64 s[68:69], s[68:69], 14
	v_and_b32_e32 v96, 0x3f0, v96
	s_add_u32 s68, s33, s68
	s_addc_u32 s69, s37, s69
	global_load_dwordx4 v[232:235], v96, s[66:67] nt
	global_load_dwordx4 v[236:239], v96, s[68:69] nt
	v_add_u32_e32 v98, 0x400, v96
	global_load_dwordx4 v[184:187], v98, s[66:67] nt
	global_load_dwordx4 v[180:183], v98, s[68:69] nt
	v_add_u32_e32 v98, 0x800, v96
	global_load_dwordx4 v[176:179], v98, s[66:67] nt
	global_load_dwordx4 v[172:175], v98, s[68:69] nt
	v_add_u32_e32 v98, 0xc00, v96
	global_load_dwordx4 v[168:171], v98, s[66:67] nt
	global_load_dwordx4 v[164:167], v98, s[68:69] nt
	v_add_u32_e32 v98, 0x1000, v96
	global_load_dwordx4 v[160:163], v98, s[66:67] nt
	global_load_dwordx4 v[156:159], v98, s[68:69] nt
	v_add_u32_e32 v98, 0x1400, v96
	global_load_dwordx4 v[152:155], v98, s[66:67] nt
	global_load_dwordx4 v[148:151], v98, s[68:69] nt
	v_add_u32_e32 v98, 0x1800, v96
	global_load_dwordx4 v[136:139], v98, s[66:67] nt
	global_load_dwordx4 v[132:135], v98, s[68:69] nt
	v_add_u32_e32 v98, 0x1c00, v96
	global_load_dwordx4 v[140:143], v98, s[66:67] nt
	global_load_dwordx4 v[144:147], v98, s[68:69] nt
	s_waitcnt vmcnt(0)
	v_lshlrev_b32_e32 v231, 16, v233
	v_lshlrev_b32_e32 v98, 16, v232
	v_and_b32_e32 v99, 0xffff0000, v232
	v_rcp_f32_e32 v232, v231
	v_and_b32_e32 v231, 0xffff0000, v233
	v_rcp_f32_e32 v233, v231
	v_rcp_f32_e32 v98, v98
	v_rcp_f32_e32 v99, v99
	v_lshlrev_b32_e32 v240, 16, v236
	v_and_b32_e32 v241, 0xffff0000, v236
	v_lshlrev_b32_e32 v236, 16, v237
	v_and_b32_e32 v237, 0xffff0000, v237
	v_pk_mul_f32 v[232:233], v[232:233], v[236:237]
	v_pk_mul_f32 v[98:99], v[98:99], v[240:241]
	v_pk_mul_f32 v[130:131], v[130:131], v[232:233]
	v_lshlrev_b32_e32 v232, 16, v180
	v_and_b32_e32 v233, 0xffff0000, v180
	v_lshlrev_b32_e32 v180, 16, v185
	v_pk_mul_f32 v[128:129], v[128:129], v[98:99]
	v_lshlrev_b32_e32 v98, 16, v184
	v_and_b32_e32 v99, 0xffff0000, v184
	v_rcp_f32_e32 v184, v180
	v_and_b32_e32 v180, 0xffff0000, v185
	v_rcp_f32_e32 v185, v180
	v_rcp_f32_e32 v98, v98
	v_rcp_f32_e32 v99, v99
	v_lshlrev_b32_e32 v180, 16, v181
	v_and_b32_e32 v181, 0xffff0000, v181
	v_pk_mul_f32 v[180:181], v[184:185], v[180:181]
	v_pk_mul_f32 v[98:99], v[98:99], v[232:233]
	v_pk_mul_f32 v[126:127], v[126:127], v[180:181]
	v_lshlrev_b32_e32 v180, 16, v172
	v_and_b32_e32 v181, 0xffff0000, v172
	v_lshlrev_b32_e32 v172, 16, v177
	v_pk_mul_f32 v[124:125], v[124:125], v[98:99]
	v_lshlrev_b32_e32 v98, 16, v176
	v_and_b32_e32 v99, 0xffff0000, v176
	v_rcp_f32_e32 v176, v172
	v_and_b32_e32 v172, 0xffff0000, v177
	v_rcp_f32_e32 v98, v98
	v_rcp_f32_e32 v99, v99
	v_rcp_f32_e32 v177, v172
	v_lshlrev_b32_e32 v172, 16, v173
	v_and_b32_e32 v173, 0xffff0000, v173
	v_pk_mul_f32 v[98:99], v[98:99], v[180:181]
	v_pk_mul_f32 v[172:173], v[176:177], v[172:173]
	v_pk_mul_f32 v[112:113], v[112:113], v[98:99]
	v_pk_mul_f32 v[114:115], v[114:115], v[172:173]
	v_lshlrev_b32_e32 v98, 16, v168
	v_and_b32_e32 v99, 0xffff0000, v168
	v_lshlrev_b32_e32 v172, 16, v164
	v_and_b32_e32 v173, 0xffff0000, v164
	v_lshlrev_b32_e32 v164, 16, v169
	v_rcp_f32_e32 v98, v98
	v_rcp_f32_e32 v99, v99
	v_rcp_f32_e32 v168, v164
	v_and_b32_e32 v164, 0xffff0000, v169
	v_rcp_f32_e32 v169, v164
	v_pk_mul_f32 v[98:99], v[98:99], v[172:173]
	v_lshlrev_b32_e32 v164, 16, v165
	v_and_b32_e32 v165, 0xffff0000, v165
	v_pk_mul_f32 v[164:165], v[168:169], v[164:165]
	v_pk_mul_f32 v[104:105], v[104:105], v[98:99]
	v_lshlrev_b32_e32 v98, 16, v160
	v_and_b32_e32 v99, 0xffff0000, v160
	v_pk_mul_f32 v[106:107], v[106:107], v[164:165]
	v_rcp_f32_e32 v98, v98
	v_rcp_f32_e32 v99, v99
	v_lshlrev_b32_e32 v164, 16, v156
	v_and_b32_e32 v165, 0xffff0000, v156
	v_lshlrev_b32_e32 v156, 16, v161
	v_rcp_f32_e32 v160, v156
	v_and_b32_e32 v156, 0xffff0000, v161
	v_rcp_f32_e32 v161, v156
	v_pk_mul_f32 v[98:99], v[98:99], v[164:165]
	v_lshlrev_b32_e32 v156, 16, v157
	v_and_b32_e32 v157, 0xffff0000, v157
	v_pk_mul_f32 v[92:93], v[92:93], v[98:99]
	v_lshlrev_b32_e32 v98, 16, v152
	v_and_b32_e32 v99, 0xffff0000, v152
	v_pk_mul_f32 v[156:157], v[160:161], v[156:157]
	v_rcp_f32_e32 v98, v98
	v_rcp_f32_e32 v99, v99
	v_pk_mul_f32 v[94:95], v[94:95], v[156:157]
	v_lshlrev_b32_e32 v156, 16, v148
	v_and_b32_e32 v157, 0xffff0000, v148
	v_lshlrev_b32_e32 v148, 16, v153
	v_rcp_f32_e32 v152, v148
	v_and_b32_e32 v148, 0xffff0000, v153
	v_rcp_f32_e32 v153, v148
	v_pk_mul_f32 v[98:99], v[98:99], v[156:157]
	v_lshlrev_b32_e32 v148, 16, v149
	v_pk_mul_f32 v[84:85], v[84:85], v[98:99]
	v_lshlrev_b32_e32 v98, 16, v136
	v_and_b32_e32 v99, 0xffff0000, v136
	v_and_b32_e32 v149, 0xffff0000, v149
	v_rcp_f32_e32 v98, v98
	v_rcp_f32_e32 v99, v99
	v_pk_mul_f32 v[148:149], v[152:153], v[148:149]
	v_lshlrev_b32_e32 v176, 16, v178
	v_pk_mul_f32 v[86:87], v[86:87], v[148:149]
	v_lshlrev_b32_e32 v148, 16, v132
	v_and_b32_e32 v149, 0xffff0000, v132
	v_lshlrev_b32_e32 v132, 16, v137
	v_rcp_f32_e32 v136, v132
	v_and_b32_e32 v132, 0xffff0000, v137
	v_pk_mul_f32 v[98:99], v[98:99], v[148:149]
	v_rcp_f32_e32 v137, v132
	v_pk_mul_f32 v[76:77], v[76:77], v[98:99]
	v_lshlrev_b32_e32 v98, 16, v140
	v_and_b32_e32 v99, 0xffff0000, v140
	v_and_b32_e32 v177, 0xffff0000, v178
	v_lshlrev_b32_e32 v180, 16, v174
; __device__ __forceinline__ float bf_lo(unsigned w) { return __uint_as_float(w << 16); }
; __device__ __forceinline__ float bf_hi(unsigned w) { return __uint_as_float(w & 0xffff0000u); }
; #define RT(a, b) ((b) * __builtin_amdgcn_rcpf(a))
;     __device__ __forceinline__ void hook(f32x4 (&acc)[2][2][4][2], const Unit& u, int which, int wr, int wc, int fr, int fq) const {
;     ...
;                     for (int bj = 0; bj < 2; ++bj) { const unsigned off = off0 + (unsigned)(((ai * 4 + m) * 2 + bj) * 1024);
;                         gnv[m][bj] = *(const u32x4*)(gn_b + off); gdv[m][bj] = *(const u32x4*)(gd_b + off); }
; #pragma unroll
;                 for (int m = 0; m < 4; ++m)
; #pragma unroll
;                     for (int bj = 0; bj < 2; ++bj) { const u32x4 gn = gnv[m][bj], gd = gdv[m][bj];
;     ...
;                         f32x4 r0, r1;
;                         r0[0] = RT(bf_lo(gn.x), bf_lo(gd.x)); r0[1] = RT(bf_hi(gn.x), bf_hi(gd.x)); r0[2] = RT(bf_lo(gn.y), bf_lo(gd.y)); r0[3] = RT(bf_hi(gn.y), bf_hi(gd.y));
;                         r1[0] = RT(bf_lo(gn.z), bf_lo(gd.z)); r1[1] = RT(bf_hi(gn.z), bf_hi(gd.z)); r1[2] = RT(bf_lo(gn.w), bf_lo(gd.w)); r1[3] = RT(bf_hi(gn.w), bf_hi(gd.w));
;     ...
;                         acc[ai][bj][m][0] *= r0; acc[ai][bj][m][1] *= r1; }
	v_and_b32_e32 v181, 0xffff0000, v174
	v_lshlrev_b32_e32 v174, 16, v179
	v_lshlrev_b32_e32 v168, 16, v170
	v_and_b32_e32 v169, 0xffff0000, v170
	v_lshlrev_b32_e32 v172, 16, v166
	v_and_b32_e32 v173, 0xffff0000, v166
	v_lshlrev_b32_e32 v166, 16, v171
	v_rcp_f32_e32 v98, v98
	v_rcp_f32_e32 v99, v99
	v_rcp_f32_e32 v176, v176
	v_rcp_f32_e32 v177, v177
	v_rcp_f32_e32 v178, v174
	v_and_b32_e32 v174, 0xffff0000, v179
	v_rcp_f32_e32 v168, v168
	v_rcp_f32_e32 v169, v169
	v_rcp_f32_e32 v170, v166
	v_and_b32_e32 v166, 0xffff0000, v171
	v_lshlrev_b32_e32 v132, 16, v133
	v_and_b32_e32 v133, 0xffff0000, v133
	v_rcp_f32_e32 v179, v174
	v_rcp_f32_e32 v171, v166
	v_pk_mul_f32 v[132:133], v[136:137], v[132:133]
	v_lshlrev_b32_e32 v232, 16, v182
	v_pk_mul_f32 v[78:79], v[78:79], v[132:133]
	v_lshlrev_b32_e32 v132, 16, v144
	v_and_b32_e32 v133, 0xffff0000, v144
	v_pk_mul_f32 v[98:99], v[98:99], v[132:133]
	v_and_b32_e32 v233, 0xffff0000, v182
	v_lshlrev_b32_e32 v182, 16, v187
	v_pk_mul_f32 v[176:177], v[176:177], v[180:181]
	v_lshlrev_b32_e32 v174, 16, v175
	v_and_b32_e32 v175, 0xffff0000, v175
	v_pk_mul_f32 v[168:169], v[168:169], v[172:173]
	v_lshlrev_b32_e32 v166, 16, v167
	v_and_b32_e32 v167, 0xffff0000, v167
	v_pk_mul_f32 v[68:69], v[68:69], v[98:99]
	v_add_u32_e32 v98, 0x2000, v96
	v_lshlrev_b32_e32 v184, 16, v186
	v_and_b32_e32 v185, 0xffff0000, v186
	v_rcp_f32_e32 v186, v182
	v_and_b32_e32 v182, 0xffff0000, v187
	v_pk_mul_f32 v[174:175], v[178:179], v[174:175]
	v_pk_mul_f32 v[108:109], v[108:109], v[176:177]
	v_pk_mul_f32 v[166:167], v[170:171], v[166:167]
	v_pk_mul_f32 v[100:101], v[100:101], v[168:169]
	global_load_dwordx4 v[168:171], v98, s[66:67] nt
	global_load_dwordx4 v[176:179], v98, s[68:69] nt
	v_rcp_f32_e32 v184, v184
	v_rcp_f32_e32 v185, v185
	v_rcp_f32_e32 v187, v182
	v_lshlrev_b32_e32 v231, 16, v234
	v_lshlrev_b32_e32 v182, 16, v183
	v_and_b32_e32 v183, 0xffff0000, v183
	v_rcp_f32_e32 v236, v231
	v_and_b32_e32 v231, 0xffff0000, v234
	v_pk_mul_f32 v[184:185], v[184:185], v[232:233]
	v_pk_mul_f32 v[182:183], v[186:187], v[182:183]
	v_add_u32_e32 v98, 0x2400, v96
	v_rcp_f32_e32 v237, v231
	v_lshlrev_b32_e32 v231, 16, v235
	v_pk_mul_f32 v[118:119], v[118:119], v[182:183]
	v_pk_mul_f32 v[116:117], v[116:117], v[184:185]
	global_load_dwordx4 v[180:183], v98, s[66:67] nt
	global_load_dwordx4 v[184:187], v98, s[68:69] nt
	v_rcp_f32_e32 v234, v231
	v_and_b32_e32 v231, 0xffff0000, v235
	v_rcp_f32_e32 v235, v231
	v_lshlrev_b32_e32 v240, 16, v238
	v_and_b32_e32 v241, 0xffff0000, v238
	v_lshlrev_b32_e32 v238, 16, v239
	v_and_b32_e32 v239, 0xffff0000, v239
	v_pk_mul_f32 v[236:237], v[236:237], v[240:241]
	v_pk_mul_f32 v[234:235], v[234:235], v[238:239]
	v_add_u32_e32 v98, 0x2800, v96
	v_pk_mul_f32 v[122:123], v[122:123], v[234:235]
	v_pk_mul_f32 v[120:121], v[120:121], v[236:237]
	global_load_dwordx4 v[232:235], v98, s[66:67] nt
	global_load_dwordx4 v[236:239], v98, s[68:69] nt
	v_lshlrev_b32_e32 v160, 16, v162
	v_and_b32_e32 v161, 0xffff0000, v162
	v_rcp_f32_e32 v160, v160
	v_rcp_f32_e32 v161, v161
	v_lshlrev_b32_e32 v164, 16, v158
	v_and_b32_e32 v165, 0xffff0000, v158
	v_add_u32_e32 v98, 0x2c00, v96
	v_pk_mul_f32 v[110:111], v[110:111], v[174:175]
	v_pk_mul_f32 v[102:103], v[102:103], v[166:167]
	v_pk_mul_f32 v[160:161], v[160:161], v[164:165]
	global_load_dwordx4 v[172:175], v98, s[66:67] nt
	global_load_dwordx4 v[164:167], v98, s[68:69] nt
	v_lshlrev_b32_e32 v158, 16, v163
	v_rcp_f32_e32 v162, v158
	v_and_b32_e32 v158, 0xffff0000, v163
	v_rcp_f32_e32 v163, v158
	v_lshlrev_b32_e32 v152, 16, v154
	v_and_b32_e32 v153, 0xffff0000, v154
	v_rcp_f32_e32 v152, v152
	v_rcp_f32_e32 v153, v153
	v_lshlrev_b32_e32 v158, 16, v159
	v_and_b32_e32 v159, 0xffff0000, v159
	v_pk_mul_f32 v[158:159], v[162:163], v[158:159]
	v_lshlrev_b32_e32 v156, 16, v150
	v_and_b32_e32 v157, 0xffff0000, v150
	v_add_u32_e32 v98, 0x3000, v96
	v_pk_mul_f32 v[90:91], v[90:91], v[158:159]
	v_pk_mul_f32 v[88:89], v[88:89], v[160:161]
	v_pk_mul_f32 v[152:153], v[152:153], v[156:157]
	v_lshlrev_b32_e32 v150, 16, v155
	global_load_dwordx4 v[160:163], v98, s[66:67] nt
	global_load_dwordx4 v[156:159], v98, s[68:69] nt
	v_rcp_f32_e32 v154, v150
	v_and_b32_e32 v150, 0xffff0000, v155
	v_lshlrev_b32_e32 v148, 16, v134
	v_and_b32_e32 v149, 0xffff0000, v134
	v_lshlrev_b32_e32 v134, 16, v139
	v_rcp_f32_e32 v155, v150
	v_lshlrev_b32_e32 v136, 16, v138
	v_and_b32_e32 v137, 0xffff0000, v138
	v_rcp_f32_e32 v138, v134
	v_and_b32_e32 v134, 0xffff0000, v139
	v_rcp_f32_e32 v136, v136
	v_rcp_f32_e32 v137, v137
	v_rcp_f32_e32 v139, v134
	v_lshlrev_b32_e32 v132, 16, v141
	v_and_b32_e32 v133, 0xffff0000, v141
	v_lshlrev_b32_e32 v150, 16, v151
	v_and_b32_e32 v151, 0xffff0000, v151
	v_rcp_f32_e32 v132, v132
	v_rcp_f32_e32 v133, v133
	v_pk_mul_f32 v[150:151], v[154:155], v[150:151]
	v_lshlrev_b32_e32 v134, 16, v135
	v_and_b32_e32 v135, 0xffff0000, v135
	v_add_u32_e32 v98, 0x3400, v96
	v_pk_mul_f32 v[82:83], v[82:83], v[150:151]
	v_pk_mul_f32 v[80:81], v[80:81], v[152:153]
	v_pk_mul_f32 v[136:137], v[136:137], v[148:149]
	v_pk_mul_f32 v[134:135], v[138:139], v[134:135]
	global_load_dwordx4 v[152:155], v98, s[66:67] nt
	global_load_dwordx4 v[148:151], v98, s[68:69] nt
	v_pk_mul_f32 v[74:75], v[74:75], v[134:135]
	v_lshlrev_b32_e32 v134, 16, v145
	v_and_b32_e32 v135, 0xffff0000, v145
	v_pk_mul_f32 v[132:133], v[132:133], v[134:135]
	v_lshlrev_b32_e32 v134, 16, v142
	v_and_b32_e32 v135, 0xffff0000, v142
	v_rcp_f32_e32 v134, v134
	v_rcp_f32_e32 v135, v135
	v_pk_mul_f32 v[72:73], v[72:73], v[136:137]
	v_lshlrev_b32_e32 v136, 16, v146
	v_and_b32_e32 v137, 0xffff0000, v146
	v_add_u32_e32 v98, 0x3800, v96
	v_pk_mul_f32 v[134:135], v[134:135], v[136:137]
	v_lshlrev_b32_e32 v136, 16, v143
	v_and_b32_e32 v137, 0xffff0000, v143
	v_lshlrev_b32_e32 v138, 16, v147
	v_and_b32_e32 v139, 0xffff0000, v147
	global_load_dwordx4 v[144:147], v98, s[66:67] nt
	global_load_dwordx4 v[140:143], v98, s[68:69] nt
	v_rcp_f32_e32 v136, v136
	v_rcp_f32_e32 v137, v137
	v_add_u32_e32 v98, 0x3c00, v96
	v_pk_mul_f32 v[70:71], v[70:71], v[132:133]
	v_pk_mul_f32 v[64:65], v[64:65], v[134:135]
	v_pk_mul_f32 v[136:137], v[136:137], v[138:139]
	s_waitcnt vmcnt(0)
; __device__ __forceinline__ float bf_lo(unsigned w) { return __uint_as_float(w << 16); }
; __device__ __forceinline__ float bf_hi(unsigned w) { return __uint_as_float(w & 0xffff0000u); }
; #define RT(a, b) ((b) * __builtin_amdgcn_rcpf(a))
;     __device__ __forceinline__ void hook(f32x4 (&acc)[2][2][4][2], const Unit& u, int which, int wr, int wc, int fr, int fq) const {
;     ...
;                     for (int bj = 0; bj < 2; ++bj) { const u32x4 gn = gnv[m][bj], gd = gdv[m][bj];
;     ...
;                         f32x4 r0, r1;
;                         r0[0] = RT(bf_lo(gn.x), bf_lo(gd.x)); r0[1] = RT(bf_hi(gn.x), bf_hi(gd.x)); r0[2] = RT(bf_lo(gn.y), bf_lo(gd.y)); r0[3] = RT(bf_hi(gn.y), bf_hi(gd.y));
;                         r1[0] = RT(bf_lo(gn.z), bf_lo(gd.z)); r1[1] = RT(bf_hi(gn.z), bf_hi(gd.z)); r1[2] = RT(bf_lo(gn.w), bf_lo(gd.w)); r1[3] = RT(bf_hi(gn.w), bf_hi(gd.w));
;     ...
;                         acc[ai][bj][m][0] *= r0; acc[ai][bj][m][1] *= r1; }
	v_and_b32_e32 v99, 0xffff0000, v168
	v_pk_mul_f32 v[66:67], v[66:67], v[136:137]
	global_load_dwordx4 v[136:139], v98, s[66:67] nt
	global_load_dwordx4 v[132:135], v98, s[68:69] nt
	v_lshlrev_b32_e32 v98, 16, v168
	v_rcp_f32_e32 v98, v98
	v_rcp_f32_e32 v99, v99
	v_lshlrev_b32_e32 v168, 16, v169
	v_and_b32_e32 v169, 0xffff0000, v169
	v_lshlrev_b32_e32 v240, 16, v176
	v_and_b32_e32 v241, 0xffff0000, v176
	v_rcp_f32_e32 v168, v168
	v_rcp_f32_e32 v169, v169
	v_pk_mul_f32 v[98:99], v[98:99], v[240:241]
	v_lshlrev_b32_e32 v176, 16, v177
	v_pk_mul_f32 v[60:61], v[60:61], v[98:99]
	v_lshlrev_b32_e32 v98, 16, v180
	v_and_b32_e32 v99, 0xffff0000, v180
	v_and_b32_e32 v177, 0xffff0000, v177
	v_rcp_f32_e32 v98, v98
	v_rcp_f32_e32 v99, v99
	v_pk_mul_f32 v[168:169], v[168:169], v[176:177]
	v_lshlrev_b32_e32 v176, 16, v170
	v_and_b32_e32 v170, 0xffff0000, v170
	v_rcp_f32_e32 v177, v170
	v_lshlrev_b32_e32 v170, 16, v171
	v_and_b32_e32 v171, 0xffff0000, v171
	v_rcp_f32_e32 v170, v170
	v_rcp_f32_e32 v171, v171
	v_pk_mul_f32 v[62:63], v[62:63], v[168:169]
	v_lshlrev_b32_e32 v168, 16, v184
	v_and_b32_e32 v169, 0xffff0000, v184
	v_pk_mul_f32 v[98:99], v[98:99], v[168:169]
	v_lshlrev_b32_e32 v168, 16, v181
	v_and_b32_e32 v169, 0xffff0000, v181
	v_rcp_f32_e32 v168, v168
	v_rcp_f32_e32 v169, v169
	v_lshlrev_b32_e32 v240, 16, v178
	v_and_b32_e32 v241, 0xffff0000, v178
	v_lshlrev_b32_e32 v178, 16, v179
	v_and_b32_e32 v179, 0xffff0000, v179
	v_pk_mul_f32 v[52:53], v[52:53], v[98:99]
	v_lshlrev_b32_e32 v98, 16, v232
	v_and_b32_e32 v99, 0xffff0000, v232
	v_pk_mul_f32 v[170:171], v[170:171], v[178:179]
	v_rcp_f32_e32 v98, v98
	v_rcp_f32_e32 v99, v99
	v_rcp_f32_e32 v176, v176
	v_pk_mul_f32 v[58:59], v[58:59], v[170:171]
	v_lshlrev_b32_e32 v170, 16, v185
	v_and_b32_e32 v171, 0xffff0000, v185
	v_pk_mul_f32 v[168:169], v[168:169], v[170:171]
	v_lshlrev_b32_e32 v170, 16, v182
	v_and_b32_e32 v171, 0xffff0000, v182
	v_rcp_f32_e32 v170, v170
	v_rcp_f32_e32 v171, v171
	v_pk_mul_f32 v[54:55], v[54:55], v[168:169]
	v_lshlrev_b32_e32 v168, 16, v236
	v_and_b32_e32 v169, 0xffff0000, v236
	v_pk_mul_f32 v[98:99], v[98:99], v[168:169]
	v_lshlrev_b32_e32 v168, 16, v233
	v_and_b32_e32 v169, 0xffff0000, v233
	v_pk_mul_f32 v[176:177], v[176:177], v[240:241]
	v_rcp_f32_e32 v168, v168
	v_rcp_f32_e32 v169, v169
	v_pk_mul_f32 v[56:57], v[56:57], v[176:177]
	v_lshlrev_b32_e32 v176, 16, v186
	v_and_b32_e32 v177, 0xffff0000, v186
	v_pk_mul_f32 v[44:45], v[44:45], v[98:99]
	v_lshlrev_b32_e32 v98, 16, v172
	v_and_b32_e32 v99, 0xffff0000, v172
	v_pk_mul_f32 v[170:171], v[170:171], v[176:177]
	v_rcp_f32_e32 v98, v98
	v_rcp_f32_e32 v99, v99
	v_pk_mul_f32 v[48:49], v[48:49], v[170:171]
	v_lshlrev_b32_e32 v170, 16, v237
	v_and_b32_e32 v171, 0xffff0000, v237
	v_pk_mul_f32 v[168:169], v[168:169], v[170:171]
	v_lshlrev_b32_e32 v176, 16, v183
	v_pk_mul_f32 v[46:47], v[46:47], v[168:169]
	v_lshlrev_b32_e32 v168, 16, v164
	v_and_b32_e32 v169, 0xffff0000, v164
	v_lshlrev_b32_e32 v164, 16, v173
	v_pk_mul_f32 v[98:99], v[98:99], v[168:169]
	v_rcp_f32_e32 v168, v164
	v_and_b32_e32 v164, 0xffff0000, v173
	v_rcp_f32_e32 v169, v164
	v_lshlrev_b32_e32 v164, 16, v165
	v_and_b32_e32 v165, 0xffff0000, v165
	v_pk_mul_f32 v[36:37], v[36:37], v[98:99]
	v_pk_mul_f32 v[164:165], v[168:169], v[164:165]
	v_lshlrev_b32_e32 v98, 16, v160
	v_pk_mul_f32 v[38:39], v[38:39], v[164:165]
	v_lshlrev_b32_e32 v164, 16, v156
	v_and_b32_e32 v165, 0xffff0000, v156
	v_lshlrev_b32_e32 v156, 16, v161
	v_and_b32_e32 v99, 0xffff0000, v160
	v_rcp_f32_e32 v160, v156
	v_and_b32_e32 v156, 0xffff0000, v161
	v_rcp_f32_e32 v161, v156
	v_rcp_f32_e32 v98, v98
	v_rcp_f32_e32 v99, v99
	v_lshlrev_b32_e32 v156, 16, v157
	v_and_b32_e32 v157, 0xffff0000, v157
	v_pk_mul_f32 v[156:157], v[160:161], v[156:157]
	v_pk_mul_f32 v[98:99], v[98:99], v[164:165]
	v_pk_mul_f32 v[30:31], v[30:31], v[156:157]
	v_lshlrev_b32_e32 v156, 16, v148
	v_and_b32_e32 v157, 0xffff0000, v148
	v_lshlrev_b32_e32 v148, 16, v153
	v_pk_mul_f32 v[28:29], v[28:29], v[98:99]
	v_lshlrev_b32_e32 v98, 16, v152
	v_and_b32_e32 v99, 0xffff0000, v152
	v_rcp_f32_e32 v152, v148
	v_and_b32_e32 v148, 0xffff0000, v153
	v_rcp_f32_e32 v153, v148
	v_rcp_f32_e32 v98, v98
	v_rcp_f32_e32 v99, v99
	v_lshlrev_b32_e32 v148, 16, v149
	v_and_b32_e32 v149, 0xffff0000, v149
	v_pk_mul_f32 v[148:149], v[152:153], v[148:149]
	v_pk_mul_f32 v[98:99], v[98:99], v[156:157]
	v_pk_mul_f32 v[22:23], v[22:23], v[148:149]
	v_lshlrev_b32_e32 v148, 16, v140
	v_and_b32_e32 v149, 0xffff0000, v140
	v_lshlrev_b32_e32 v140, 16, v145
	v_pk_mul_f32 v[20:21], v[20:21], v[98:99]
	v_lshlrev_b32_e32 v98, 16, v144
	v_and_b32_e32 v99, 0xffff0000, v144
	v_rcp_f32_e32 v144, v140
	v_and_b32_e32 v140, 0xffff0000, v145
	v_rcp_f32_e32 v98, v98
	v_rcp_f32_e32 v99, v99
	v_rcp_f32_e32 v145, v140
	v_and_b32_e32 v177, 0xffff0000, v183
	v_rcp_f32_e32 v176, v176
	v_rcp_f32_e32 v177, v177
	v_lshlrev_b32_e32 v140, 16, v141
	v_and_b32_e32 v141, 0xffff0000, v141
	v_lshlrev_b32_e32 v170, 16, v234
	v_and_b32_e32 v171, 0xffff0000, v234
	v_pk_mul_f32 v[98:99], v[98:99], v[148:149]
	v_pk_mul_f32 v[140:141], v[144:145], v[140:141]
	v_rcp_f32_e32 v170, v170
	v_rcp_f32_e32 v171, v171
	v_pk_mul_f32 v[18:19], v[18:19], v[140:141]
	v_pk_mul_f32 v[16:17], v[16:17], v[98:99]
	s_waitcnt vmcnt(0)
; __device__ __forceinline__ float bf_lo(unsigned w) { return __uint_as_float(w << 16); }
; __device__ __forceinline__ float bf_hi(unsigned w) { return __uint_as_float(w & 0xffff0000u); }
; #define RT(a, b) ((b) * __builtin_amdgcn_rcpf(a))
;     __device__ __forceinline__ void hook(f32x4 (&acc)[2][2][4][2], const Unit& u, int which, int wr, int wc, int fr, int fq) const {
;     ...
;                     for (int bj = 0; bj < 2; ++bj) { const u32x4 gn = gnv[m][bj], gd = gdv[m][bj];
;     ...
;                         f32x4 r0, r1;
;                         r0[0] = RT(bf_lo(gn.x), bf_lo(gd.x)); r0[1] = RT(bf_hi(gn.x), bf_hi(gd.x)); r0[2] = RT(bf_lo(gn.y), bf_lo(gd.y)); r0[3] = RT(bf_hi(gn.y), bf_hi(gd.y));
;                         r1[0] = RT(bf_lo(gn.z), bf_lo(gd.z)); r1[1] = RT(bf_hi(gn.z), bf_hi(gd.z)); r1[2] = RT(bf_lo(gn.w), bf_lo(gd.w)); r1[3] = RT(bf_hi(gn.w), bf_hi(gd.w));
;     ...
;                         acc[ai][bj][m][0] *= r0; acc[ai][bj][m][1] *= r1; }
	v_lshlrev_b32_e32 v98, 16, v136
	v_and_b32_e32 v99, 0xffff0000, v136
	v_lshlrev_b32_e32 v140, 16, v132
	v_and_b32_e32 v141, 0xffff0000, v132
	v_lshlrev_b32_e32 v132, 16, v137
	v_lshlrev_b32_e32 v178, 16, v187
	v_and_b32_e32 v179, 0xffff0000, v187
	v_lshlrev_b32_e32 v168, 16, v174
	v_and_b32_e32 v169, 0xffff0000, v174
	v_rcp_f32_e32 v98, v98
	v_rcp_f32_e32 v99, v99
	v_rcp_f32_e32 v136, v132
	v_and_b32_e32 v132, 0xffff0000, v137
	v_pk_mul_f32 v[176:177], v[176:177], v[178:179]
	v_rcp_f32_e32 v168, v168
	v_rcp_f32_e32 v169, v169
	v_rcp_f32_e32 v137, v132
	v_pk_mul_f32 v[50:51], v[50:51], v[176:177]
	v_lshlrev_b32_e32 v176, 16, v238
	v_and_b32_e32 v177, 0xffff0000, v238
	v_pk_mul_f32 v[170:171], v[170:171], v[176:177]
	v_lshlrev_b32_e32 v164, 16, v158
	v_pk_mul_f32 v[40:41], v[40:41], v[170:171]
	v_lshlrev_b32_e32 v170, 16, v166
	v_and_b32_e32 v171, 0xffff0000, v166
	v_lshlrev_b32_e32 v166, 16, v175
	v_and_b32_e32 v165, 0xffff0000, v158
	v_lshlrev_b32_e32 v158, 16, v163
	v_lshlrev_b32_e32 v156, 16, v150
	v_and_b32_e32 v157, 0xffff0000, v150
	v_lshlrev_b32_e32 v150, 16, v155
	v_lshlrev_b32_e32 v148, 16, v142
	v_and_b32_e32 v149, 0xffff0000, v142
	v_lshlrev_b32_e32 v142, 16, v147
	v_pk_mul_f32 v[98:99], v[98:99], v[140:141]
	v_lshlrev_b32_e32 v132, 16, v133
	v_and_b32_e32 v133, 0xffff0000, v133
	v_lshlrev_b32_e32 v140, 16, v134
	v_and_b32_e32 v141, 0xffff0000, v134
	v_lshlrev_b32_e32 v134, 16, v139
	v_lshlrev_b32_e32 v176, 16, v235
	v_and_b32_e32 v177, 0xffff0000, v235
	v_pk_mul_f32 v[168:169], v[168:169], v[170:171]
	v_rcp_f32_e32 v170, v166
	v_and_b32_e32 v166, 0xffff0000, v175
	v_lshlrev_b32_e32 v160, 16, v162
	v_and_b32_e32 v161, 0xffff0000, v162
	v_rcp_f32_e32 v162, v158
	v_and_b32_e32 v158, 0xffff0000, v163
	v_lshlrev_b32_e32 v152, 16, v154
	v_and_b32_e32 v153, 0xffff0000, v154
	v_rcp_f32_e32 v154, v150
	v_and_b32_e32 v150, 0xffff0000, v155
	v_lshlrev_b32_e32 v144, 16, v146
	v_and_b32_e32 v145, 0xffff0000, v146
	v_rcp_f32_e32 v146, v142
	v_and_b32_e32 v142, 0xffff0000, v147
	v_pk_mul_f32 v[132:133], v[136:137], v[132:133]
	v_lshlrev_b32_e32 v136, 16, v138
	v_and_b32_e32 v137, 0xffff0000, v138
	v_rcp_f32_e32 v138, v134
	v_and_b32_e32 v134, 0xffff0000, v139
	v_rcp_f32_e32 v176, v176
	v_rcp_f32_e32 v177, v177
	v_rcp_f32_e32 v171, v166
	v_rcp_f32_e32 v160, v160
	v_rcp_f32_e32 v161, v161
	v_rcp_f32_e32 v163, v158
	v_rcp_f32_e32 v152, v152
	v_rcp_f32_e32 v153, v153
	v_rcp_f32_e32 v155, v150
	v_rcp_f32_e32 v144, v144
	v_rcp_f32_e32 v145, v145
	v_rcp_f32_e32 v147, v142
	v_rcp_f32_e32 v136, v136
	v_rcp_f32_e32 v137, v137
	v_rcp_f32_e32 v139, v134
	v_lshlrev_b32_e32 v178, 16, v239
	v_and_b32_e32 v179, 0xffff0000, v239
	v_lshlrev_b32_e32 v166, 16, v167
	v_and_b32_e32 v167, 0xffff0000, v167
	v_lshlrev_b32_e32 v158, 16, v159
	v_and_b32_e32 v159, 0xffff0000, v159
	v_lshlrev_b32_e32 v150, 16, v151
	v_and_b32_e32 v151, 0xffff0000, v151
	v_lshlrev_b32_e32 v142, 16, v143
	v_and_b32_e32 v143, 0xffff0000, v143
	v_lshlrev_b32_e32 v134, 16, v135
	v_and_b32_e32 v135, 0xffff0000, v135
	v_pk_mul_f32 v[176:177], v[176:177], v[178:179]
	v_pk_mul_f32 v[166:167], v[170:171], v[166:167]
	v_pk_mul_f32 v[160:161], v[160:161], v[164:165]
	v_pk_mul_f32 v[158:159], v[162:163], v[158:159]
	v_pk_mul_f32 v[152:153], v[152:153], v[156:157]
	v_pk_mul_f32 v[150:151], v[154:155], v[150:151]
	v_pk_mul_f32 v[144:145], v[144:145], v[148:149]
	v_pk_mul_f32 v[142:143], v[146:147], v[142:143]
	v_pk_mul_f32 v[136:137], v[136:137], v[140:141]
	v_pk_mul_f32 v[134:135], v[138:139], v[134:135]
	v_pk_mul_f32 v[42:43], v[42:43], v[176:177]
	v_pk_mul_f32 v[34:35], v[34:35], v[166:167]
	v_pk_mul_f32 v[32:33], v[32:33], v[168:169]
	v_pk_mul_f32 v[26:27], v[26:27], v[158:159]
	v_pk_mul_f32 v[24:25], v[24:25], v[160:161]
	v_pk_mul_f32 v[14:15], v[14:15], v[150:151]
	v_pk_mul_f32 v[12:13], v[12:13], v[152:153]
	v_pk_mul_f32 v[10:11], v[10:11], v[142:143]
	v_pk_mul_f32 v[8:9], v[8:9], v[144:145]
	v_pk_mul_f32 v[6:7], v[6:7], v[132:133]
	v_pk_mul_f32 v[4:5], v[4:5], v[98:99]
	v_pk_mul_f32 v[2:3], v[2:3], v[134:135]
	v_pk_mul_f32 v[0:1], v[0:1], v[136:137]

; __device__ __forceinline__ float bf_lo(unsigned w) { return __uint_as_float(w << 16); }
; __device__ __forceinline__ float bf_hi(unsigned w) { return __uint_as_float(w & 0xffff0000u); }
; __device__ __forceinline__ unsigned cvt_pk_bf16(float lo, float hi) { f32x2_t v = {lo, hi}; bf16x2_t b = __builtin_convertvector(v, bf16x2_t); return __builtin_bit_cast(unsigned, b); }
; #define EPI_LANE() int t__ = threadIdx.x; asm volatile("" : "+v"(t__)); const int wid__ = __builtin_amdgcn_readfirstlane(t__ >> 6); wr = wid__ >> 2; wc = wid__ & 3; fr = t__ & 15; fq = (t__ & 63) >> 4
;     __device__ __forceinline__ void operator()(const f32x4 (&acc)[2][2][4][2], const Unit& u, int wr, int wc, int fr, int fq) const {
;         EPI_LANE();
;         const char* g_b = gbase(2, u, wid__) + (t__ & 63) * 16; char* mb = (char*)(Mg + (size_t)u.pm * BM * 1024 + u.pn * BM);
;         unsigned rl0 = (unsigned)(wr * 64 + fr), cl0 = (unsigned)(wc * 32 + 8 * fq); asm volatile("" : "+v"(rl0), "+v"(cl0));
; #pragma unroll
;         for (int ai = 0; ai < 2; ++ai) {
;             u32x4 gv[4][2];
; #pragma unroll
;             for (int m = 0; m < 4; ++m)
; #pragma unroll
;                 for (int bj = 0; bj < 2; ++bj) gv[m][bj] = *(const u32x4*)(g_b + ((ai * 4 + m) * 2 + bj) * 1024);
; #pragma unroll
;             for (int m = 0; m < 4; ++m) { const unsigned rl = rl0 + (unsigned)(ai * HALF + m * 16);
; #pragma unroll
;                 for (int bj = 0; bj < 2; ++bj) { const unsigned cl = cl0 + (unsigned)(bj * HALF);
;                     const u32x4 g = gv[m][bj];
;                     const f32x4 v0 = acc[ai][bj][m][0], v1 = acc[ai][bj][m][1];
;                     u32x4 w;
;                     w.x = cvt_pk_bf16(v0[0] * __builtin_amdgcn_rcpf(bf_lo(g.x)), v0[1] * __builtin_amdgcn_rcpf(bf_hi(g.x)));
;                     w.y = cvt_pk_bf16(v0[2] * __builtin_amdgcn_rcpf(bf_lo(g.y)), v0[3] * __builtin_amdgcn_rcpf(bf_hi(g.y)));
;                     w.z = cvt_pk_bf16(v1[0] * __builtin_amdgcn_rcpf(bf_lo(g.z)), v1[1] * __builtin_amdgcn_rcpf(bf_hi(g.z)));
;                     w.w = cvt_pk_bf16(v1[2] * __builtin_amdgcn_rcpf(bf_lo(g.w)), v1[3] * __builtin_amdgcn_rcpf(bf_hi(g.w)));
;                     *(u32x4*)(mb + (rl * 1024u + cl) * 2u) = w; } }
.LBB0_57:
	v_mov_b32_e32 v132, v212
	s_lshl_b32 s61, s6, 10
	v_readfirstlane_b32 s31, v132
	s_lshl_b32 s62, s60, 3
	s_ashr_i32 s36, s31, 6
	s_add_i32 s61, s61, s62
	s_add_i32 s61, s61, s36
	s_add_i32 s62, s61, 0x2000
	s_ashr_i32 s63, s62, 31
	s_lshl_b64 s[62:63], s[62:63], 14
	s_add_u32 s62, s33, s62
	s_addc_u32 s63, s37, s63
	s_ashr_i32 s61, s60, 31
	s_lshl_b64 s[60:61], s[60:61], 19
	s_add_u32 s64, s89, s60
	s_addc_u32 s65, s3, s61
	s_lshl_b32 s60, s6, 8
	s_ashr_i32 s61, s60, 31
	s_lshl_b64 s[60:61], s[60:61], 1
	s_add_u32 s60, s64, s60
	s_addc_u32 s61, s65, s61
	s_ashr_i32 s6, s31, 2
	s_andn2_b32 s6, s6, 63
	v_and_or_b32 v158, v132, 15, s6
	s_lshl_b32 s6, s36, 5
	v_lshlrev_b32_e32 v96, 4, v132
	s_and_b32 s6, s6, 0x60
	v_lshrrev_b32_e32 v132, 1, v132
	v_and_b32_e32 v96, 0x3f0, v96
	v_and_or_b32 v159, v132, 24, s6
	global_load_dwordx4 v[160:163], v96, s[62:63] nt
	global_load_dwordx4 v[164:167], v96, s[62:63] offset:1024 nt
	global_load_dwordx4 v[152:155], v96, s[62:63] offset:2048 nt
	global_load_dwordx4 v[148:151], v96, s[62:63] offset:3072 nt
	v_lshl_add_u64 v[98:99], s[62:63], 0, v[96:97]
	s_movk_i32 s6, 0x1000
	v_add_co_u32_e32 v132, vcc, s6, v98
	s_movk_i32 s6, 0x2000
	s_nop 0
	v_addc_co_u32_e32 v133, vcc, 0, v99, vcc
	v_add_co_u32_e32 v156, vcc, s6, v98
	v_lshlrev_b32_e32 v96, 1, v159
	s_nop 0
	v_addc_co_u32_e32 v157, vcc, 0, v99, vcc
	global_load_dwordx4 v[144:147], v[156:157], off offset:-4096 nt
	global_load_dwordx4 v[140:143], v[132:133], off offset:1024 nt
	global_load_dwordx4 v[136:139], v[132:133], off offset:2048 nt
	s_nop 0
	global_load_dwordx4 v[132:135], v[132:133], off offset:3072 nt
	v_lshl_add_u32 v96, v158, 11, v96
	s_movk_i32 s6, 0x3000
	s_waitcnt vmcnt(0)
	v_lshlrev_b32_e32 v168, 16, v160
	v_and_b32_e32 v160, 0xffff0000, v160
	v_rcp_f32_e32 v168, v168
	v_rcp_f32_e32 v169, v160
	s_nop 0
	v_pk_mul_f32 v[128:129], v[128:129], v[168:169]
	s_nop 0
	v_cvt_pk_bf16_f32 v128, v128, v129
	v_lshlrev_b32_e32 v129, 16, v161
	v_rcp_f32_e32 v160, v129
	v_and_b32_e32 v129, 0xffff0000, v161
	v_rcp_f32_e32 v161, v129
	s_nop 0
	v_pk_mul_f32 v[130:131], v[130:131], v[160:161]
	s_nop 0
	v_cvt_pk_bf16_f32 v129, v130, v131
	v_lshlrev_b32_e32 v130, 16, v162
	v_and_b32_e32 v131, 0xffff0000, v162
	v_rcp_f32_e32 v130, v130
	v_rcp_f32_e32 v131, v131
	s_nop 0
	v_pk_mul_f32 v[120:121], v[120:121], v[130:131]
	s_nop 0
	v_cvt_pk_bf16_f32 v130, v120, v121
	v_lshlrev_b32_e32 v120, 16, v163
	v_and_b32_e32 v121, 0xffff0000, v163
	v_rcp_f32_e32 v120, v120
	v_rcp_f32_e32 v121, v121
	s_nop 0
	v_pk_mul_f32 v[120:121], v[122:123], v[120:121]
	s_nop 0
	v_cvt_pk_bf16_f32 v131, v120, v121
	v_lshlrev_b32_e32 v120, 16, v164
	v_and_b32_e32 v121, 0xffff0000, v164
	v_rcp_f32_e32 v120, v120
	v_rcp_f32_e32 v121, v121
	global_store_dwordx4 v96, v[128:131], s[60:61]
	v_pk_mul_f32 v[120:121], v[124:125], v[120:121]
	s_nop 0
	v_cvt_pk_bf16_f32 v120, v120, v121
	v_lshlrev_b32_e32 v121, 16, v165
	v_rcp_f32_e32 v122, v121
	v_and_b32_e32 v121, 0xffff0000, v165
	v_rcp_f32_e32 v123, v121
	s_nop 0
	v_pk_mul_f32 v[122:123], v[126:127], v[122:123]
	s_nop 0
	v_cvt_pk_bf16_f32 v121, v122, v123
	v_lshlrev_b32_e32 v122, 16, v166
	v_and_b32_e32 v123, 0xffff0000, v166
	v_rcp_f32_e32 v122, v122
	v_rcp_f32_e32 v123, v123
	s_nop 0
	v_pk_mul_f32 v[116:117], v[116:117], v[122:123]
	s_nop 0
	v_cvt_pk_bf16_f32 v122, v116, v117
	v_lshlrev_b32_e32 v116, 16, v167
	v_and_b32_e32 v117, 0xffff0000, v167
	v_rcp_f32_e32 v116, v116
	v_rcp_f32_e32 v117, v117
	s_nop 0
	v_pk_mul_f32 v[116:117], v[118:119], v[116:117]
	s_nop 0
	v_cvt_pk_bf16_f32 v123, v116, v117
	v_add_u32_e32 v116, 0x100, v96
	global_store_dwordx4 v116, v[120:123], s[60:61]
	v_lshlrev_b32_e32 v116, 16, v152
	v_and_b32_e32 v117, 0xffff0000, v152
	v_rcp_f32_e32 v116, v116
	v_rcp_f32_e32 v117, v117
	v_add_u32_e32 v118, 0x8000, v96
	v_pk_mul_f32 v[112:113], v[112:113], v[116:117]
	s_nop 0
	v_cvt_pk_bf16_f32 v112, v112, v113
	v_lshlrev_b32_e32 v113, 16, v153
	v_rcp_f32_e32 v116, v113
	v_and_b32_e32 v113, 0xffff0000, v153
	v_rcp_f32_e32 v117, v113
	s_nop 0
	v_pk_mul_f32 v[114:115], v[114:115], v[116:117]
	s_nop 0
	v_cvt_pk_bf16_f32 v113, v114, v115
	v_lshlrev_b32_e32 v114, 16, v154
	v_and_b32_e32 v115, 0xffff0000, v154
	v_rcp_f32_e32 v114, v114
	v_rcp_f32_e32 v115, v115
	s_nop 0
	v_pk_mul_f32 v[108:109], v[108:109], v[114:115]
	s_nop 0
	v_cvt_pk_bf16_f32 v114, v108, v109
	v_lshlrev_b32_e32 v108, 16, v155
	v_and_b32_e32 v109, 0xffff0000, v155
	v_rcp_f32_e32 v108, v108
	v_rcp_f32_e32 v109, v109
	s_nop 0
	v_pk_mul_f32 v[108:109], v[110:111], v[108:109]
	s_nop 0
	v_cvt_pk_bf16_f32 v115, v108, v109
	v_lshlrev_b32_e32 v108, 16, v148
	v_and_b32_e32 v109, 0xffff0000, v148
	v_rcp_f32_e32 v108, v108
	v_rcp_f32_e32 v109, v109
	global_store_dwordx4 v118, v[112:115], s[60:61]
	v_pk_mul_f32 v[104:105], v[104:105], v[108:109]
	s_nop 0
	v_cvt_pk_bf16_f32 v104, v104, v105
	v_lshlrev_b32_e32 v105, 16, v149
	v_rcp_f32_e32 v108, v105
	v_and_b32_e32 v105, 0xffff0000, v149
	v_rcp_f32_e32 v109, v105
	s_nop 0
	v_pk_mul_f32 v[106:107], v[106:107], v[108:109]
	s_nop 0
	v_cvt_pk_bf16_f32 v105, v106, v107
	v_lshlrev_b32_e32 v106, 16, v150
	v_and_b32_e32 v107, 0xffff0000, v150
	v_rcp_f32_e32 v106, v106
	v_rcp_f32_e32 v107, v107
	s_nop 0
	v_pk_mul_f32 v[100:101], v[100:101], v[106:107]
	s_nop 0
	v_cvt_pk_bf16_f32 v106, v100, v101
	v_lshlrev_b32_e32 v100, 16, v151
	v_and_b32_e32 v101, 0xffff0000, v151
	v_rcp_f32_e32 v100, v100
	v_rcp_f32_e32 v101, v101
	s_nop 0
	v_pk_mul_f32 v[100:101], v[102:103], v[100:101]
	s_nop 0
	v_cvt_pk_bf16_f32 v107, v100, v101
	v_add_u32_e32 v100, 0x8100, v96
	global_store_dwordx4 v100, v[104:107], s[60:61]
	v_lshlrev_b32_e32 v100, 16, v144
; __device__ __forceinline__ float bf_lo(unsigned w) { return __uint_as_float(w << 16); }
; __device__ __forceinline__ float bf_hi(unsigned w) { return __uint_as_float(w & 0xffff0000u); }
; __device__ __forceinline__ unsigned cvt_pk_bf16(float lo, float hi) { f32x2_t v = {lo, hi}; bf16x2_t b = __builtin_convertvector(v, bf16x2_t); return __builtin_bit_cast(unsigned, b); }
;     __device__ __forceinline__ void operator()(const f32x4 (&acc)[2][2][4][2], const Unit& u, int wr, int wc, int fr, int fq) const {
;     ...
;                 for (int bj = 0; bj < 2; ++bj) gv[m][bj] = *(const u32x4*)(g_b + ((ai * 4 + m) * 2 + bj) * 1024);
; #pragma unroll
;             for (int m = 0; m < 4; ++m) { const unsigned rl = rl0 + (unsigned)(ai * HALF + m * 16);
; #pragma unroll
;                 for (int bj = 0; bj < 2; ++bj) { const unsigned cl = cl0 + (unsigned)(bj * HALF);
;                     const u32x4 g = gv[m][bj];
;                     const f32x4 v0 = acc[ai][bj][m][0], v1 = acc[ai][bj][m][1];
;                     u32x4 w;
;                     w.x = cvt_pk_bf16(v0[0] * __builtin_amdgcn_rcpf(bf_lo(g.x)), v0[1] * __builtin_amdgcn_rcpf(bf_hi(g.x)));
;                     w.y = cvt_pk_bf16(v0[2] * __builtin_amdgcn_rcpf(bf_lo(g.y)), v0[3] * __builtin_amdgcn_rcpf(bf_hi(g.y)));
;                     w.z = cvt_pk_bf16(v1[0] * __builtin_amdgcn_rcpf(bf_lo(g.z)), v1[1] * __builtin_amdgcn_rcpf(bf_hi(g.z)));
;                     w.w = cvt_pk_bf16(v1[2] * __builtin_amdgcn_rcpf(bf_lo(g.w)), v1[3] * __builtin_amdgcn_rcpf(bf_hi(g.w)));
;                     *(u32x4*)(mb + (rl * 1024u + cl) * 2u) = w; } }
	v_and_b32_e32 v101, 0xffff0000, v144
	v_rcp_f32_e32 v100, v100
	v_rcp_f32_e32 v101, v101
	v_add_u32_e32 v102, 0x10000, v96
	v_pk_mul_f32 v[92:93], v[92:93], v[100:101]
	s_nop 0
	v_cvt_pk_bf16_f32 v92, v92, v93
	v_lshlrev_b32_e32 v93, 16, v145
	v_rcp_f32_e32 v100, v93
	v_and_b32_e32 v93, 0xffff0000, v145
	v_rcp_f32_e32 v101, v93
	s_nop 0
	v_pk_mul_f32 v[94:95], v[94:95], v[100:101]
	s_nop 0
	v_cvt_pk_bf16_f32 v93, v94, v95
	v_lshlrev_b32_e32 v94, 16, v146
	v_and_b32_e32 v95, 0xffff0000, v146
	v_rcp_f32_e32 v94, v94
	v_rcp_f32_e32 v95, v95
	s_nop 0
	v_pk_mul_f32 v[88:89], v[88:89], v[94:95]
	s_nop 0
	v_cvt_pk_bf16_f32 v94, v88, v89
	v_lshlrev_b32_e32 v88, 16, v147
	v_and_b32_e32 v89, 0xffff0000, v147
	v_rcp_f32_e32 v88, v88
	v_rcp_f32_e32 v89, v89
	s_nop 0
	v_pk_mul_f32 v[88:89], v[90:91], v[88:89]
	s_nop 0
	v_cvt_pk_bf16_f32 v95, v88, v89
	v_lshlrev_b32_e32 v88, 16, v140
	v_and_b32_e32 v89, 0xffff0000, v140
	v_rcp_f32_e32 v88, v88
	v_rcp_f32_e32 v89, v89
	global_store_dwordx4 v102, v[92:95], s[60:61]
	v_pk_mul_f32 v[84:85], v[84:85], v[88:89]
	s_nop 0
	v_cvt_pk_bf16_f32 v84, v84, v85
	v_lshlrev_b32_e32 v85, 16, v141
	v_rcp_f32_e32 v88, v85
	v_and_b32_e32 v85, 0xffff0000, v141
	v_rcp_f32_e32 v89, v85
	s_nop 0
	v_pk_mul_f32 v[86:87], v[86:87], v[88:89]
	s_nop 0
	v_cvt_pk_bf16_f32 v85, v86, v87
	v_lshlrev_b32_e32 v86, 16, v142
	v_and_b32_e32 v87, 0xffff0000, v142
	v_rcp_f32_e32 v86, v86
	v_rcp_f32_e32 v87, v87
	s_nop 0
	v_pk_mul_f32 v[80:81], v[80:81], v[86:87]
	s_nop 0
	v_cvt_pk_bf16_f32 v86, v80, v81
	v_lshlrev_b32_e32 v80, 16, v143
	v_and_b32_e32 v81, 0xffff0000, v143
	v_rcp_f32_e32 v80, v80
	v_rcp_f32_e32 v81, v81
	s_nop 0
	v_pk_mul_f32 v[80:81], v[82:83], v[80:81]
	s_nop 0
	v_cvt_pk_bf16_f32 v87, v80, v81
	v_add_u32_e32 v80, 0x10100, v96
	global_store_dwordx4 v80, v[84:87], s[60:61]
	v_lshlrev_b32_e32 v80, 16, v136
	v_and_b32_e32 v81, 0xffff0000, v136
	v_rcp_f32_e32 v80, v80
	v_rcp_f32_e32 v81, v81
	v_add_u32_e32 v82, 0x18000, v96
	v_pk_mul_f32 v[76:77], v[76:77], v[80:81]
	s_nop 0
	v_cvt_pk_bf16_f32 v76, v76, v77
	v_lshlrev_b32_e32 v77, 16, v137
	v_rcp_f32_e32 v80, v77
	v_and_b32_e32 v77, 0xffff0000, v137
	v_rcp_f32_e32 v81, v77
	s_nop 0
	v_pk_mul_f32 v[78:79], v[78:79], v[80:81]
	s_nop 0
	v_cvt_pk_bf16_f32 v77, v78, v79
	v_lshlrev_b32_e32 v78, 16, v138
	v_and_b32_e32 v79, 0xffff0000, v138
	v_rcp_f32_e32 v78, v78
	v_rcp_f32_e32 v79, v79
	s_nop 0
	v_pk_mul_f32 v[72:73], v[72:73], v[78:79]
	s_nop 0
	v_cvt_pk_bf16_f32 v78, v72, v73
	v_lshlrev_b32_e32 v72, 16, v139
	v_and_b32_e32 v73, 0xffff0000, v139
	v_rcp_f32_e32 v72, v72
	v_rcp_f32_e32 v73, v73
	s_nop 0
	v_pk_mul_f32 v[72:73], v[74:75], v[72:73]
	s_nop 0
	v_cvt_pk_bf16_f32 v79, v72, v73
	v_lshlrev_b32_e32 v72, 16, v132
	v_and_b32_e32 v73, 0xffff0000, v132
	v_rcp_f32_e32 v72, v72
	v_rcp_f32_e32 v73, v73
	global_store_dwordx4 v82, v[76:79], s[60:61]
	v_pk_mul_f32 v[68:69], v[68:69], v[72:73]
	s_nop 0
	v_cvt_pk_bf16_f32 v68, v68, v69
	v_lshlrev_b32_e32 v69, 16, v133
	v_rcp_f32_e32 v72, v69
	v_and_b32_e32 v69, 0xffff0000, v133
	v_rcp_f32_e32 v73, v69
	s_nop 0
	v_pk_mul_f32 v[70:71], v[70:71], v[72:73]
	s_nop 0
	v_cvt_pk_bf16_f32 v69, v70, v71
	v_lshlrev_b32_e32 v70, 16, v134
	v_and_b32_e32 v71, 0xffff0000, v134
	v_rcp_f32_e32 v70, v70
	v_rcp_f32_e32 v71, v71
	s_nop 0
	v_pk_mul_f32 v[64:65], v[64:65], v[70:71]
	s_nop 0
	v_cvt_pk_bf16_f32 v70, v64, v65
	v_lshlrev_b32_e32 v64, 16, v135
	v_and_b32_e32 v65, 0xffff0000, v135
	v_rcp_f32_e32 v64, v64
	v_rcp_f32_e32 v65, v65
	s_nop 0
	v_pk_mul_f32 v[64:65], v[66:67], v[64:65]
	s_nop 0
	v_cvt_pk_bf16_f32 v71, v64, v65
	v_add_u32_e32 v64, 0x18100, v96
	global_store_dwordx4 v64, v[68:71], s[60:61]
	global_load_dwordx4 v[90:93], v[156:157], off nt
	global_load_dwordx4 v[100:103], v[156:157], off offset:1024 nt
	global_load_dwordx4 v[84:87], v[156:157], off offset:2048 nt
	global_load_dwordx4 v[80:83], v[156:157], off offset:3072 nt
	v_add_co_u32_e32 v64, vcc, s6, v98
	v_lshlrev_b32_e32 v88, 11, v158
	s_nop 0
	v_addc_co_u32_e32 v65, vcc, 0, v99, vcc
	global_load_dwordx4 v[76:79], v[64:65], off nt
	global_load_dwordx4 v[72:75], v[64:65], off offset:1024 nt
	global_load_dwordx4 v[68:71], v[64:65], off offset:2048 nt
	s_nop 0
	global_load_dwordx4 v[64:67], v[64:65], off offset:3072 nt
	v_lshl_add_u32 v88, v159, 1, v88
	v_add_u32_e32 v89, 0x40000, v88
	s_and_b64 vcc, exec, s[38:39]
	s_waitcnt vmcnt(0)
; __device__ __forceinline__ float bf_lo(unsigned w) { return __uint_as_float(w << 16); }
; __device__ __forceinline__ float bf_hi(unsigned w) { return __uint_as_float(w & 0xffff0000u); }
; __device__ __forceinline__ unsigned cvt_pk_bf16(float lo, float hi) { f32x2_t v = {lo, hi}; bf16x2_t b = __builtin_convertvector(v, bf16x2_t); return __builtin_bit_cast(unsigned, b); }
;     __device__ __forceinline__ void operator()(const f32x4 (&acc)[2][2][4][2], const Unit& u, int wr, int wc, int fr, int fq) const {
;     ...
;             for (int m = 0; m < 4; ++m) { const unsigned rl = rl0 + (unsigned)(ai * HALF + m * 16);
; #pragma unroll
;                 for (int bj = 0; bj < 2; ++bj) { const unsigned cl = cl0 + (unsigned)(bj * HALF);
;                     const u32x4 g = gv[m][bj];
;                     const f32x4 v0 = acc[ai][bj][m][0], v1 = acc[ai][bj][m][1];
;                     u32x4 w;
;                     w.x = cvt_pk_bf16(v0[0] * __builtin_amdgcn_rcpf(bf_lo(g.x)), v0[1] * __builtin_amdgcn_rcpf(bf_hi(g.x)));
;                     w.y = cvt_pk_bf16(v0[2] * __builtin_amdgcn_rcpf(bf_lo(g.y)), v0[3] * __builtin_amdgcn_rcpf(bf_hi(g.y)));
;                     w.z = cvt_pk_bf16(v1[0] * __builtin_amdgcn_rcpf(bf_lo(g.z)), v1[1] * __builtin_amdgcn_rcpf(bf_hi(g.z)));
;                     w.w = cvt_pk_bf16(v1[2] * __builtin_amdgcn_rcpf(bf_lo(g.w)), v1[3] * __builtin_amdgcn_rcpf(bf_hi(g.w)));
;                     *(u32x4*)(mb + (rl * 1024u + cl) * 2u) = w; } }
	v_lshlrev_b32_e32 v94, 16, v90
	v_and_b32_e32 v90, 0xffff0000, v90
	v_rcp_f32_e32 v94, v94
	v_rcp_f32_e32 v95, v90
	s_nop 0
	v_pk_mul_f32 v[60:61], v[60:61], v[94:95]
	s_nop 0
	v_cvt_pk_bf16_f32 v60, v60, v61
	v_lshlrev_b32_e32 v61, 16, v91
	v_rcp_f32_e32 v90, v61
	v_and_b32_e32 v61, 0xffff0000, v91
	v_rcp_f32_e32 v91, v61
	s_nop 0
	v_pk_mul_f32 v[62:63], v[62:63], v[90:91]
	s_nop 0
	v_cvt_pk_bf16_f32 v61, v62, v63
	v_lshlrev_b32_e32 v62, 16, v92
	v_and_b32_e32 v63, 0xffff0000, v92
	v_rcp_f32_e32 v62, v62
	v_rcp_f32_e32 v63, v63
	s_nop 0
	v_pk_mul_f32 v[56:57], v[56:57], v[62:63]
	s_nop 0
	v_cvt_pk_bf16_f32 v62, v56, v57
	v_lshlrev_b32_e32 v56, 16, v93
	v_and_b32_e32 v57, 0xffff0000, v93
	v_rcp_f32_e32 v56, v56
	v_rcp_f32_e32 v57, v57
	s_nop 0
	v_pk_mul_f32 v[56:57], v[58:59], v[56:57]
	s_nop 0
	v_cvt_pk_bf16_f32 v63, v56, v57
	v_lshlrev_b32_e32 v56, 16, v100
	v_and_b32_e32 v57, 0xffff0000, v100
	v_rcp_f32_e32 v56, v56
	v_rcp_f32_e32 v57, v57
	global_store_dwordx4 v89, v[60:63], s[60:61]
	v_pk_mul_f32 v[52:53], v[52:53], v[56:57]
	s_nop 0
	v_cvt_pk_bf16_f32 v52, v52, v53
	v_lshlrev_b32_e32 v53, 16, v101
	v_rcp_f32_e32 v56, v53
	v_and_b32_e32 v53, 0xffff0000, v101
	v_rcp_f32_e32 v57, v53
	s_nop 0
	v_pk_mul_f32 v[54:55], v[54:55], v[56:57]
	s_nop 0
	v_cvt_pk_bf16_f32 v53, v54, v55
	v_lshlrev_b32_e32 v54, 16, v102
	v_and_b32_e32 v55, 0xffff0000, v102
	v_rcp_f32_e32 v54, v54
	v_rcp_f32_e32 v55, v55
	s_nop 0
	v_pk_mul_f32 v[48:49], v[48:49], v[54:55]
	s_nop 0
	v_cvt_pk_bf16_f32 v54, v48, v49
	v_lshlrev_b32_e32 v48, 16, v103
	v_and_b32_e32 v49, 0xffff0000, v103
	v_rcp_f32_e32 v48, v48
	v_rcp_f32_e32 v49, v49
	s_nop 0
	v_pk_mul_f32 v[48:49], v[50:51], v[48:49]
	s_nop 0
	v_cvt_pk_bf16_f32 v55, v48, v49
	v_add_u32_e32 v48, 0x40100, v88
	global_store_dwordx4 v48, v[52:55], s[60:61]
	v_lshlrev_b32_e32 v48, 16, v84
	v_and_b32_e32 v49, 0xffff0000, v84
	v_rcp_f32_e32 v48, v48
	v_rcp_f32_e32 v49, v49
	v_add_u32_e32 v50, 0x48000, v88
	v_pk_mul_f32 v[44:45], v[44:45], v[48:49]
	s_nop 0
	v_cvt_pk_bf16_f32 v44, v44, v45
	v_lshlrev_b32_e32 v45, 16, v85
	v_rcp_f32_e32 v48, v45
	v_and_b32_e32 v45, 0xffff0000, v85
	v_rcp_f32_e32 v49, v45
	s_nop 0
	v_pk_mul_f32 v[46:47], v[46:47], v[48:49]
	s_nop 0
	v_cvt_pk_bf16_f32 v45, v46, v47
	v_lshlrev_b32_e32 v46, 16, v86
	v_and_b32_e32 v47, 0xffff0000, v86
	v_rcp_f32_e32 v46, v46
	v_rcp_f32_e32 v47, v47
	s_nop 0
	v_pk_mul_f32 v[40:41], v[40:41], v[46:47]
	s_nop 0
	v_cvt_pk_bf16_f32 v46, v40, v41
	v_lshlrev_b32_e32 v40, 16, v87
	v_and_b32_e32 v41, 0xffff0000, v87
	v_rcp_f32_e32 v40, v40
	v_rcp_f32_e32 v41, v41
	s_nop 0
	v_pk_mul_f32 v[40:41], v[42:43], v[40:41]
	s_nop 0
	v_cvt_pk_bf16_f32 v47, v40, v41
	v_lshlrev_b32_e32 v40, 16, v80
	v_and_b32_e32 v41, 0xffff0000, v80
	v_rcp_f32_e32 v40, v40
	v_rcp_f32_e32 v41, v41
	global_store_dwordx4 v50, v[44:47], s[60:61]
	v_pk_mul_f32 v[36:37], v[36:37], v[40:41]
	s_nop 0
	v_cvt_pk_bf16_f32 v36, v36, v37
	v_lshlrev_b32_e32 v37, 16, v81
	v_rcp_f32_e32 v40, v37
	v_and_b32_e32 v37, 0xffff0000, v81
	v_rcp_f32_e32 v41, v37
	s_nop 0
	v_pk_mul_f32 v[38:39], v[38:39], v[40:41]
	s_nop 0
	v_cvt_pk_bf16_f32 v37, v38, v39
	v_lshlrev_b32_e32 v38, 16, v82
	v_and_b32_e32 v39, 0xffff0000, v82
	v_rcp_f32_e32 v38, v38
	v_rcp_f32_e32 v39, v39
	s_nop 0
	v_pk_mul_f32 v[32:33], v[32:33], v[38:39]
	s_nop 0
	v_cvt_pk_bf16_f32 v38, v32, v33
	v_lshlrev_b32_e32 v32, 16, v83
	v_and_b32_e32 v33, 0xffff0000, v83
	v_rcp_f32_e32 v32, v32
	v_rcp_f32_e32 v33, v33
	s_nop 0
	v_pk_mul_f32 v[32:33], v[34:35], v[32:33]
	s_nop 0
	v_cvt_pk_bf16_f32 v39, v32, v33
	v_add_u32_e32 v32, 0x48100, v88
	global_store_dwordx4 v32, v[36:39], s[60:61]
	v_lshlrev_b32_e32 v32, 16, v76
; __device__ __forceinline__ float bf_lo(unsigned w) { return __uint_as_float(w << 16); }
; __device__ __forceinline__ float bf_hi(unsigned w) { return __uint_as_float(w & 0xffff0000u); }
; __device__ __forceinline__ unsigned cvt_pk_bf16(float lo, float hi) { f32x2_t v = {lo, hi}; bf16x2_t b = __builtin_convertvector(v, bf16x2_t); return __builtin_bit_cast(unsigned, b); }
;     __device__ __forceinline__ void operator()(const f32x4 (&acc)[2][2][4][2], const Unit& u, int wr, int wc, int fr, int fq) const {
;     ...
;             for (int m = 0; m < 4; ++m) { const unsigned rl = rl0 + (unsigned)(ai * HALF + m * 16);
; #pragma unroll
;                 for (int bj = 0; bj < 2; ++bj) { const unsigned cl = cl0 + (unsigned)(bj * HALF);
;                     const u32x4 g = gv[m][bj];
;                     const f32x4 v0 = acc[ai][bj][m][0], v1 = acc[ai][bj][m][1];
;                     u32x4 w;
;                     w.x = cvt_pk_bf16(v0[0] * __builtin_amdgcn_rcpf(bf_lo(g.x)), v0[1] * __builtin_amdgcn_rcpf(bf_hi(g.x)));
;                     w.y = cvt_pk_bf16(v0[2] * __builtin_amdgcn_rcpf(bf_lo(g.y)), v0[3] * __builtin_amdgcn_rcpf(bf_hi(g.y)));
;                     w.z = cvt_pk_bf16(v1[0] * __builtin_amdgcn_rcpf(bf_lo(g.z)), v1[1] * __builtin_amdgcn_rcpf(bf_hi(g.z)));
;                     w.w = cvt_pk_bf16(v1[2] * __builtin_amdgcn_rcpf(bf_lo(g.w)), v1[3] * __builtin_amdgcn_rcpf(bf_hi(g.w)));
;                     *(u32x4*)(mb + (rl * 1024u + cl) * 2u) = w; } }
;             asm volatile("" : "+v"(rl0), "+v"(cl0) :: "memory"); }
	v_and_b32_e32 v33, 0xffff0000, v76
	v_rcp_f32_e32 v32, v32
	v_rcp_f32_e32 v33, v33
	v_add_u32_e32 v34, 0x50000, v88
	v_pk_mul_f32 v[28:29], v[28:29], v[32:33]
	s_nop 0
	v_cvt_pk_bf16_f32 v28, v28, v29
	v_lshlrev_b32_e32 v29, 16, v77
	v_rcp_f32_e32 v32, v29
	v_and_b32_e32 v29, 0xffff0000, v77
	v_rcp_f32_e32 v33, v29
	s_nop 0
	v_pk_mul_f32 v[30:31], v[30:31], v[32:33]
	s_nop 0
	v_cvt_pk_bf16_f32 v29, v30, v31
	v_lshlrev_b32_e32 v30, 16, v78
	v_and_b32_e32 v31, 0xffff0000, v78
	v_rcp_f32_e32 v30, v30
	v_rcp_f32_e32 v31, v31
	s_nop 0
	v_pk_mul_f32 v[24:25], v[24:25], v[30:31]
	s_nop 0
	v_cvt_pk_bf16_f32 v30, v24, v25
	v_lshlrev_b32_e32 v24, 16, v79
	v_and_b32_e32 v25, 0xffff0000, v79
	v_rcp_f32_e32 v24, v24
	v_rcp_f32_e32 v25, v25
	s_nop 0
	v_pk_mul_f32 v[24:25], v[26:27], v[24:25]
	s_nop 0
	v_cvt_pk_bf16_f32 v31, v24, v25
	v_lshlrev_b32_e32 v24, 16, v72
	v_and_b32_e32 v25, 0xffff0000, v72
	v_rcp_f32_e32 v24, v24
	v_rcp_f32_e32 v25, v25
	global_store_dwordx4 v34, v[28:31], s[60:61]
	v_pk_mul_f32 v[20:21], v[20:21], v[24:25]
	s_nop 0
	v_cvt_pk_bf16_f32 v20, v20, v21
	v_lshlrev_b32_e32 v21, 16, v73
	v_rcp_f32_e32 v24, v21
	v_and_b32_e32 v21, 0xffff0000, v73
	v_rcp_f32_e32 v25, v21
	s_nop 0
	v_pk_mul_f32 v[22:23], v[22:23], v[24:25]
	s_nop 0
	v_cvt_pk_bf16_f32 v21, v22, v23
	v_lshlrev_b32_e32 v22, 16, v74
	v_and_b32_e32 v23, 0xffff0000, v74
	v_rcp_f32_e32 v22, v22
	v_rcp_f32_e32 v23, v23
	s_nop 0
	v_pk_mul_f32 v[12:13], v[12:13], v[22:23]
	s_nop 0
	v_cvt_pk_bf16_f32 v22, v12, v13
	v_lshlrev_b32_e32 v12, 16, v75
	v_and_b32_e32 v13, 0xffff0000, v75
	v_rcp_f32_e32 v12, v12
	v_rcp_f32_e32 v13, v13
	s_nop 0
	v_pk_mul_f32 v[12:13], v[14:15], v[12:13]
	s_nop 0
	v_cvt_pk_bf16_f32 v23, v12, v13
	v_add_u32_e32 v12, 0x50100, v88
	global_store_dwordx4 v12, v[20:23], s[60:61]
	v_lshlrev_b32_e32 v12, 16, v68
	v_and_b32_e32 v13, 0xffff0000, v68
	v_rcp_f32_e32 v12, v12
	v_rcp_f32_e32 v13, v13
	v_add_u32_e32 v20, 0x58000, v88
	v_pk_mul_f32 v[12:13], v[16:17], v[12:13]
	s_nop 0
	v_cvt_pk_bf16_f32 v12, v12, v13
	v_lshlrev_b32_e32 v13, 16, v69
	v_rcp_f32_e32 v14, v13
	v_and_b32_e32 v13, 0xffff0000, v69
	v_rcp_f32_e32 v15, v13
	s_nop 0
	v_pk_mul_f32 v[14:15], v[18:19], v[14:15]
	s_nop 0
	v_cvt_pk_bf16_f32 v13, v14, v15
	v_lshlrev_b32_e32 v14, 16, v70
	v_and_b32_e32 v15, 0xffff0000, v70
	v_rcp_f32_e32 v14, v14
	v_rcp_f32_e32 v15, v15
	s_nop 0
	v_pk_mul_f32 v[8:9], v[8:9], v[14:15]
	s_nop 0
	v_cvt_pk_bf16_f32 v14, v8, v9
	v_lshlrev_b32_e32 v8, 16, v71
	v_and_b32_e32 v9, 0xffff0000, v71
	v_rcp_f32_e32 v8, v8
	v_rcp_f32_e32 v9, v9
	s_nop 0
	v_pk_mul_f32 v[8:9], v[10:11], v[8:9]
	s_nop 0
	v_cvt_pk_bf16_f32 v15, v8, v9
	v_lshlrev_b32_e32 v8, 16, v64
	v_and_b32_e32 v9, 0xffff0000, v64
	v_rcp_f32_e32 v8, v8
	v_rcp_f32_e32 v9, v9
	global_store_dwordx4 v20, v[12:15], s[60:61]
	v_pk_mul_f32 v[4:5], v[4:5], v[8:9]
	s_nop 0
	v_cvt_pk_bf16_f32 v4, v4, v5
	v_lshlrev_b32_e32 v5, 16, v65
	v_rcp_f32_e32 v8, v5
	v_and_b32_e32 v5, 0xffff0000, v65
	v_rcp_f32_e32 v9, v5
	s_nop 0
	v_pk_mul_f32 v[6:7], v[6:7], v[8:9]
	s_nop 0
	v_cvt_pk_bf16_f32 v5, v6, v7
	v_lshlrev_b32_e32 v6, 16, v66
	v_and_b32_e32 v7, 0xffff0000, v66
	v_rcp_f32_e32 v6, v6
	v_rcp_f32_e32 v7, v7
	s_nop 0
	v_pk_mul_f32 v[0:1], v[0:1], v[6:7]
	s_nop 0
	v_cvt_pk_bf16_f32 v6, v0, v1
	v_lshlrev_b32_e32 v0, 16, v67
	v_and_b32_e32 v1, 0xffff0000, v67
	v_rcp_f32_e32 v0, v0
	v_rcp_f32_e32 v1, v1
	s_nop 0
	v_pk_mul_f32 v[0:1], v[2:3], v[0:1]
	s_nop 0
	v_cvt_pk_bf16_f32 v7, v0, v1
	v_add_u32_e32 v0, 0x58100, v88
	global_store_dwordx4 v0, v[4:7], s[60:61]
	s_mov_b64 s[60:61], -1
	s_cbranch_vccnz .LBB0_35
	s_andn2_b64 vcc, exec, s[46:47]
	s_cbranch_vccnz .LBB0_34
	s_barrier
	s_branch .LBB0_34

;     __device__ __forceinline__ void operator()(const f32x4 (&acc)[2][2][4][2], const Unit& u, int wr, int wc, int fr, int fq) const {
;     ...
;             const char* sp = (const char*)(stats + (size_t)u.pm * BM * 2);
;             unsigned soff0 = (unsigned)(wr * 64 + fr) * 8u, coff0 = (unsigned)(u.pn * BM + wc * 32 + 4 * fq) * 4u; asm volatile("" : "+v"(soff0), "+v"(coff0));
;             f32x4 gv[2][2], bv[2][2];
; #pragma unroll
;             for (int bj = 0; bj < 2; ++bj)
; #pragma unroll
;                 for (int n = 0; n < 2; ++n) { gv[bj][n] = *(const f32x4*)((const char*)lng + coff0 + (unsigned)(bj * HALF + n * 16) * 4u); bv[bj][n] = *(const f32x4*)((const char*)lnb + coff0 + (unsigned)(bj * HALF + n * 16) * 4u); }
; #pragma unroll
;             for (int ai = 0; ai < 2; ++ai)
; #pragma unroll
;                 for (int mh = 0; mh < 2; ++mh) {
;                     f32x4 bs[2][2][2]; f32x2_t st[2];
; #pragma unroll
;                     for (int mm = 0; mm < 2; ++mm) { st[mm] = *(const f32x2_t*)(sp + soff0 + (unsigned)(ai * HALF + (2 * mh + mm) * 16) * 8u);
; #pragma unroll
;                         for (int bj = 0; bj < 2; ++bj)
; #pragma unroll
;                             for (int n = 0; n < 2; ++n) bs[mm][bj][n] = *(const f32x4*)(bb + off0 + (unsigned)((ai * HALF + (2 * mh + mm) * 16) * 1024 + bj * HALF + n * 16) * 4u); }
; #pragma unroll
;                     for (int mm = 0; mm < 2; ++mm)
; #pragma unroll
;                         for (int bj = 0; bj < 2; ++bj)
; #pragma unroll
;                             for (int n = 0; n < 2; ++n) { const f32x4 hv = ((bs[mm][bj][n] - st[mm][0]) * st[mm][1]) * gv[bj][n] + bv[bj][n];
;                                 *(f32x4*)(ob + off0 + (unsigned)((ai * HALF + (2 * mh + mm) * 16) * 1024 + bj * HALF + n * 16) * 4u) = hv * DN_ALPHA + acc[ai][bj][2 * mh + mm][n]; }
;                     asm volatile("" : "+v"(off0), "+v"(soff0) :: "memory"); }
.LBB0_443:
	s_ashr_i32 s71, s70, 31
	s_lshl_b32 s86, s72, 8
	v_readlane_b32 s24, v253, 0
	s_lshl_b64 s[66:67], s[70:71], 18
	s_ashr_i32 s68, s86, 31
	v_readlane_b32 s25, v253, 1
	s_add_u32 s66, s66, s86
	s_load_dwordx4 s[76:79], s[24:25], 0xa8
	s_addc_u32 s67, s67, s68
	s_lshl_b64 s[66:67], s[66:67], 2
	s_add_u32 s68, s46, s66
	v_mov_b32_e32 v96, v212
	s_addc_u32 s69, s47, s67
	s_waitcnt lgkmcnt(0)
	s_add_u32 s66, s76, s66
	v_readfirstlane_b32 s73, v96
	s_addc_u32 s67, s77, s67
	s_ashr_i32 s72, s73, 2
	s_andn2_b32 s72, s72, 63
	v_and_or_b32 v130, v96, 15, s72
	s_lshr_b32 s72, s73, 1
	v_lshrrev_b32_e32 v96, 2, v96
	v_lshlrev_b32_e32 v132, 10, v130
	s_and_b32 s87, s72, 0x60
	v_and_b32_e32 v131, 12, v96
	v_or3_b32 v96, v132, s87, v131
	v_lshlrev_b32_e32 v96, 2, v96
	s_mov_b64 s[72:73], -1
	s_and_b64 vcc, exec, s[44:45]
	s_cbranch_vccz .LBB0_445
	s_or_b32 s72, s86, s87
	s_lshl_b64 s[70:71], s[70:71], 11
	v_lshlrev_b32_e32 v190, 3, v130
	v_or_b32_e32 v130, s72, v131
	v_readlane_b32 s24, v253, 37
	v_lshlrev_b32_e32 v134, 2, v130
	s_add_u32 s70, s24, s70
	v_readlane_b32 s24, v253, 38
	s_addc_u32 s71, s24, s71
	global_load_dwordx4 v[154:157], v134, s[54:55]
	global_load_dwordx4 v[158:161], v134, s[42:43]
	global_load_dwordx4 v[146:149], v134, s[54:55] offset:64
	global_load_dwordx4 v[150:153], v134, s[42:43] offset:64
	global_load_dwordx4 v[138:141], v134, s[54:55] offset:512
	global_load_dwordx4 v[142:145], v134, s[42:43] offset:512
	global_load_dwordx4 v[130:133], v134, s[54:55] offset:576
	s_nop 0
	global_load_dwordx4 v[134:137], v134, s[42:43] offset:576
	s_nop 0
	global_load_dwordx2 v[186:187], v190, s[70:71]
	global_load_dwordx4 v[202:205], v96, s[68:69]
	global_load_dwordx4 v[206:209], v96, s[68:69] offset:64
	global_load_dwordx4 v[230:233], v96, s[68:69] offset:512
	global_load_dwordx4 v[234:237], v96, s[68:69] offset:576
	global_load_dwordx2 v[182:183], v190, s[70:71] offset:128
	v_lshl_add_u64 v[162:163], s[68:69], 0, v[96:97]
	s_mov_b32 s24, 0x10000
	v_add_co_u32_e32 v162, vcc, s24, v162
	v_lshl_add_u64 v[184:185], s[66:67], 0, v[96:97]
	s_nop 0
	v_addc_co_u32_e32 v163, vcc, 0, v163, vcc
	global_load_dwordx4 v[238:241], v[162:163], off nt
	global_load_dwordx4 v[170:173], v[162:163], off offset:64 nt
	global_load_dwordx4 v[166:169], v[162:163], off offset:512 nt
	s_nop 0
	global_load_dwordx4 v[162:165], v[162:163], off offset:576 nt
	v_add_co_u32_e32 v184, vcc, s24, v184
	s_mov_b32 s24, 0x20000
	s_nop 0
	v_addc_co_u32_e32 v185, vcc, 0, v185, vcc
	s_mov_b32 s25, 0x30000
	s_mov_b64 s[72:73], 0
	s_waitcnt vmcnt(0)
	v_sub_f32_e32 v193, v205, v186
	v_sub_f32_e32 v192, v204, v186
	v_sub_f32_e32 v203, v203, v186
	v_sub_f32_e32 v202, v202, v186
	v_pk_mul_f32 v[202:203], v[186:187], v[202:203] op_sel:[1,0]
	v_pk_mul_f32 v[192:193], v[186:187], v[192:193] op_sel:[1,0]
	v_pk_fma_f32 v[202:203], v[154:155], v[202:203], v[158:159]
	v_pk_fma_f32 v[192:193], v[156:157], v[192:193], v[160:161]
	v_pk_fma_f32 v[202:203], v[202:203], s[88:89], v[126:127] op_sel_hi:[1,0,1]
	v_pk_fma_f32 v[204:205], v[192:193], s[88:89], v[128:129] op_sel_hi:[1,0,1]
	global_store_dwordx4 v96, v[202:205], s[66:67]
	v_sub_f32_e32 v193, v209, v186
	v_sub_f32_e32 v192, v208, v186
	v_sub_f32_e32 v203, v207, v186
	v_sub_f32_e32 v202, v206, v186
	v_pk_mul_f32 v[202:203], v[186:187], v[202:203] op_sel:[1,0]
	v_pk_mul_f32 v[192:193], v[186:187], v[192:193] op_sel:[1,0]
	v_pk_fma_f32 v[202:203], v[146:147], v[202:203], v[150:151]
	v_pk_fma_f32 v[192:193], v[148:149], v[192:193], v[152:153]
	v_pk_fma_f32 v[202:203], v[202:203], s[88:89], v[122:123] op_sel_hi:[1,0,1]
	v_pk_fma_f32 v[204:205], v[192:193], s[88:89], v[124:125] op_sel_hi:[1,0,1]
	global_store_dwordx4 v96, v[202:205], s[66:67] offset:64
	v_sub_f32_e32 v193, v233, v186
	v_sub_f32_e32 v192, v232, v186
	v_sub_f32_e32 v203, v231, v186
	v_sub_f32_e32 v202, v230, v186
	v_pk_mul_f32 v[202:203], v[186:187], v[202:203] op_sel:[1,0]
	v_pk_mul_f32 v[192:193], v[186:187], v[192:193] op_sel:[1,0]
	v_pk_fma_f32 v[202:203], v[138:139], v[202:203], v[142:143]
	v_pk_fma_f32 v[192:193], v[140:141], v[192:193], v[144:145]
	v_pk_fma_f32 v[202:203], v[202:203], s[88:89], v[118:119] op_sel_hi:[1,0,1]
	v_pk_fma_f32 v[204:205], v[192:193], s[88:89], v[120:121] op_sel_hi:[1,0,1]
	global_store_dwordx4 v96, v[202:205], s[66:67] offset:512
	v_sub_f32_e32 v193, v237, v186
	v_sub_f32_e32 v192, v236, v186
	v_sub_f32_e32 v203, v235, v186
	v_sub_f32_e32 v202, v234, v186
	v_pk_mul_f32 v[202:203], v[186:187], v[202:203] op_sel:[1,0]
	v_pk_mul_f32 v[186:187], v[186:187], v[192:193] op_sel:[1,0]
	v_pk_fma_f32 v[192:193], v[130:131], v[202:203], v[134:135]
	v_pk_fma_f32 v[186:187], v[132:133], v[186:187], v[136:137]
	v_pk_fma_f32 v[202:203], v[192:193], s[88:89], v[114:115] op_sel_hi:[1,0,1]
	v_pk_fma_f32 v[204:205], v[186:187], s[88:89], v[116:117] op_sel_hi:[1,0,1]
	v_sub_f32_e32 v187, v239, v182
	v_sub_f32_e32 v186, v238, v182
	v_sub_f32_e32 v193, v241, v182
	v_sub_f32_e32 v192, v240, v182
	v_sub_f32_e32 v171, v171, v182
	v_sub_f32_e32 v170, v170, v182
	v_sub_f32_e32 v173, v173, v182
	v_sub_f32_e32 v172, v172, v182
	v_sub_f32_e32 v167, v167, v182
	v_sub_f32_e32 v166, v166, v182
	v_sub_f32_e32 v169, v169, v182
	v_sub_f32_e32 v168, v168, v182
	v_sub_f32_e32 v163, v163, v182
	v_sub_f32_e32 v162, v162, v182
	v_sub_f32_e32 v165, v165, v182
	v_sub_f32_e32 v164, v164, v182
	v_pk_mul_f32 v[192:193], v[182:183], v[192:193] op_sel:[1,0]
	v_pk_mul_f32 v[186:187], v[182:183], v[186:187] op_sel:[1,0]
	v_pk_mul_f32 v[172:173], v[182:183], v[172:173] op_sel:[1,0]
	v_pk_mul_f32 v[170:171], v[182:183], v[170:171] op_sel:[1,0]
	v_pk_mul_f32 v[168:169], v[182:183], v[168:169] op_sel:[1,0]
;     __device__ __forceinline__ void operator()(const f32x4 (&acc)[2][2][4][2], const Unit& u, int wr, int wc, int fr, int fq) const {
;     ...
;             for (int ai = 0; ai < 2; ++ai)
; #pragma unroll
;                 for (int mh = 0; mh < 2; ++mh) {
;                     f32x4 bs[2][2][2]; f32x2_t st[2];
; #pragma unroll
;                     for (int mm = 0; mm < 2; ++mm) { st[mm] = *(const f32x2_t*)(sp + soff0 + (unsigned)(ai * HALF + (2 * mh + mm) * 16) * 8u);
; #pragma unroll
;                         for (int bj = 0; bj < 2; ++bj)
; #pragma unroll
;                             for (int n = 0; n < 2; ++n) bs[mm][bj][n] = *(const f32x4*)(bb + off0 + (unsigned)((ai * HALF + (2 * mh + mm) * 16) * 1024 + bj * HALF + n * 16) * 4u); }
; #pragma unroll
;                     for (int mm = 0; mm < 2; ++mm)
; #pragma unroll
;                         for (int bj = 0; bj < 2; ++bj)
; #pragma unroll
;                             for (int n = 0; n < 2; ++n) { const f32x4 hv = ((bs[mm][bj][n] - st[mm][0]) * st[mm][1]) * gv[bj][n] + bv[bj][n];
;                                 *(f32x4*)(ob + off0 + (unsigned)((ai * HALF + (2 * mh + mm) * 16) * 1024 + bj * HALF + n * 16) * 4u) = hv * DN_ALPHA + acc[ai][bj][2 * mh + mm][n]; }
;                     asm volatile("" : "+v"(off0), "+v"(soff0) :: "memory"); }
	v_pk_mul_f32 v[166:167], v[182:183], v[166:167] op_sel:[1,0]
	v_pk_mul_f32 v[164:165], v[182:183], v[164:165] op_sel:[1,0]
	v_pk_mul_f32 v[162:163], v[182:183], v[162:163] op_sel:[1,0]
	v_pk_fma_f32 v[186:187], v[154:155], v[186:187], v[158:159]
	v_pk_fma_f32 v[192:193], v[156:157], v[192:193], v[160:161]
	v_pk_fma_f32 v[170:171], v[146:147], v[170:171], v[150:151]
	v_pk_fma_f32 v[172:173], v[148:149], v[172:173], v[152:153]
	v_pk_fma_f32 v[166:167], v[138:139], v[166:167], v[142:143]
	v_pk_fma_f32 v[168:169], v[140:141], v[168:169], v[144:145]
	v_pk_fma_f32 v[162:163], v[130:131], v[162:163], v[134:135]
	v_pk_fma_f32 v[164:165], v[132:133], v[164:165], v[136:137]
	global_store_dwordx4 v96, v[202:205], s[66:67] offset:576
	v_pk_fma_f32 v[172:173], v[172:173], s[88:89], v[108:109] op_sel_hi:[1,0,1]
	v_pk_fma_f32 v[170:171], v[170:171], s[88:89], v[106:107] op_sel_hi:[1,0,1]
	v_pk_fma_f32 v[204:205], v[192:193], s[88:89], v[112:113] op_sel_hi:[1,0,1]
	v_pk_fma_f32 v[202:203], v[186:187], s[88:89], v[110:111] op_sel_hi:[1,0,1]
	v_pk_fma_f32 v[168:169], v[168:169], s[88:89], v[104:105] op_sel_hi:[1,0,1]
	v_pk_fma_f32 v[166:167], v[166:167], s[88:89], v[102:103] op_sel_hi:[1,0,1]
	v_pk_fma_f32 v[164:165], v[164:165], s[88:89], v[100:101] op_sel_hi:[1,0,1]
	v_pk_fma_f32 v[162:163], v[162:163], s[88:89], v[98:99] op_sel_hi:[1,0,1]
	global_store_dwordx4 v[184:185], v[202:205], off
	global_store_dwordx4 v[184:185], v[170:173], off offset:64
	global_store_dwordx4 v[184:185], v[166:169], off offset:512
	global_store_dwordx4 v[184:185], v[162:165], off offset:576
	v_mov_b32_e32 v182, v96
	v_mov_b32_e32 v183, v97
	global_load_dwordx2 v[192:193], v190, s[70:71] offset:256
	v_lshl_add_u64 v[162:163], s[68:69], 0, v[182:183]
	v_add_co_u32_e32 v164, vcc, s24, v162
	v_lshl_add_u64 v[186:187], s[66:67], 0, v[182:183]
	s_nop 0
	v_addc_co_u32_e32 v165, vcc, 0, v163, vcc
	global_load_dwordx4 v[202:205], v[164:165], off nt
	global_load_dwordx4 v[206:209], v[164:165], off offset:64 nt
	global_load_dwordx4 v[230:233], v[164:165], off offset:512 nt
	global_load_dwordx4 v[234:237], v[164:165], off offset:576 nt
	global_load_dwordx2 v[184:185], v190, s[70:71] offset:384
	v_add_co_u32_e32 v162, vcc, s25, v162
	s_waitcnt vmcnt(4)
	v_sub_f32_e32 v203, v203, v192
	v_addc_co_u32_e32 v163, vcc, 0, v163, vcc
	global_load_dwordx4 v[238:241], v[162:163], off nt
	global_load_dwordx4 v[170:173], v[162:163], off offset:64 nt
	global_load_dwordx4 v[166:169], v[162:163], off offset:512 nt
	s_nop 0
	global_load_dwordx4 v[162:165], v[162:163], off offset:576 nt
	v_sub_f32_e32 v202, v202, v192
	v_sub_f32_e32 v205, v205, v192
	v_sub_f32_e32 v204, v204, v192
	v_pk_mul_f32 v[204:205], v[192:193], v[204:205] op_sel:[1,0]
	v_pk_mul_f32 v[202:203], v[192:193], v[202:203] op_sel:[1,0]
	v_pk_fma_f32 v[204:205], v[156:157], v[204:205], v[160:161]
	v_pk_fma_f32 v[202:203], v[154:155], v[202:203], v[158:159]
	v_add_co_u32_e32 v210, vcc, s24, v186
	v_pk_fma_f32 v[204:205], v[204:205], s[88:89], v[94:95] op_sel_hi:[1,0,1]
	v_pk_fma_f32 v[202:203], v[202:203], s[88:89], v[92:93] op_sel_hi:[1,0,1]
	v_addc_co_u32_e32 v211, vcc, 0, v187, vcc
	global_store_dwordx4 v[210:211], v[202:205], off
	v_add_co_u32_e32 v186, vcc, s25, v186
	s_waitcnt vmcnt(8)
	v_sub_f32_e32 v203, v207, v192
	v_sub_f32_e32 v202, v206, v192
	v_sub_f32_e32 v205, v209, v192
	v_sub_f32_e32 v204, v208, v192
	v_pk_mul_f32 v[204:205], v[192:193], v[204:205] op_sel:[1,0]
	v_pk_mul_f32 v[202:203], v[192:193], v[202:203] op_sel:[1,0]
	v_pk_fma_f32 v[204:205], v[148:149], v[204:205], v[152:153]
	v_pk_fma_f32 v[202:203], v[146:147], v[202:203], v[150:151]
	v_pk_fma_f32 v[204:205], v[204:205], s[88:89], v[90:91] op_sel_hi:[1,0,1]
	v_pk_fma_f32 v[202:203], v[202:203], s[88:89], v[88:89] op_sel_hi:[1,0,1]
	global_store_dwordx4 v[210:211], v[202:205], off offset:64
	v_addc_co_u32_e32 v187, vcc, 0, v187, vcc
	s_waitcnt vmcnt(8)
	v_sub_f32_e32 v203, v231, v192
	v_sub_f32_e32 v202, v230, v192
	v_sub_f32_e32 v205, v233, v192
	v_sub_f32_e32 v204, v232, v192
	v_pk_mul_f32 v[204:205], v[192:193], v[204:205] op_sel:[1,0]
	v_pk_mul_f32 v[202:203], v[192:193], v[202:203] op_sel:[1,0]
	v_pk_fma_f32 v[204:205], v[140:141], v[204:205], v[144:145]
	v_pk_fma_f32 v[202:203], v[138:139], v[202:203], v[142:143]
	v_pk_fma_f32 v[204:205], v[204:205], s[88:89], v[86:87] op_sel_hi:[1,0,1]
	v_pk_fma_f32 v[202:203], v[202:203], s[88:89], v[84:85] op_sel_hi:[1,0,1]
	global_store_dwordx4 v[210:211], v[202:205], off offset:512
	s_mov_b32 s24, 0x80000
	s_mov_b32 s25, 0x90000
	s_waitcnt vmcnt(8)
	v_sub_f32_e32 v203, v235, v192
	v_sub_f32_e32 v202, v234, v192
	v_sub_f32_e32 v205, v237, v192
	v_sub_f32_e32 v204, v236, v192
	v_pk_mul_f32 v[204:205], v[192:193], v[204:205] op_sel:[1,0]
	v_pk_mul_f32 v[192:193], v[192:193], v[202:203] op_sel:[1,0]
	v_pk_fma_f32 v[202:203], v[132:133], v[204:205], v[136:137]
	v_pk_fma_f32 v[192:193], v[130:131], v[192:193], v[134:135]
	v_pk_fma_f32 v[204:205], v[202:203], s[88:89], v[82:83] op_sel_hi:[1,0,1]
	v_pk_fma_f32 v[202:203], v[192:193], s[88:89], v[80:81] op_sel_hi:[1,0,1]
	global_store_dwordx4 v[210:211], v[202:205], off offset:576
	s_waitcnt vmcnt(7)
	v_sub_f32_e32 v193, v239, v184
	v_sub_f32_e32 v192, v238, v184
	v_sub_f32_e32 v203, v241, v184
	v_sub_f32_e32 v202, v240, v184
	s_waitcnt vmcnt(6)
	v_sub_f32_e32 v171, v171, v184
	v_sub_f32_e32 v170, v170, v184
	v_sub_f32_e32 v173, v173, v184
	v_sub_f32_e32 v172, v172, v184
	s_waitcnt vmcnt(5)
	v_sub_f32_e32 v167, v167, v184
	v_sub_f32_e32 v166, v166, v184
	v_sub_f32_e32 v169, v169, v184
	v_sub_f32_e32 v168, v168, v184
	s_waitcnt vmcnt(4)
;     __device__ __forceinline__ void operator()(const f32x4 (&acc)[2][2][4][2], const Unit& u, int wr, int wc, int fr, int fq) const {
;     ...
;             for (int ai = 0; ai < 2; ++ai)
; #pragma unroll
;                 for (int mh = 0; mh < 2; ++mh) {
;                     f32x4 bs[2][2][2]; f32x2_t st[2];
; #pragma unroll
;                     for (int mm = 0; mm < 2; ++mm) { st[mm] = *(const f32x2_t*)(sp + soff0 + (unsigned)(ai * HALF + (2 * mh + mm) * 16) * 8u);
; #pragma unroll
;                         for (int bj = 0; bj < 2; ++bj)
; #pragma unroll
;                             for (int n = 0; n < 2; ++n) bs[mm][bj][n] = *(const f32x4*)(bb + off0 + (unsigned)((ai * HALF + (2 * mh + mm) * 16) * 1024 + bj * HALF + n * 16) * 4u); }
; #pragma unroll
;                     for (int mm = 0; mm < 2; ++mm)
; #pragma unroll
;                         for (int bj = 0; bj < 2; ++bj)
; #pragma unroll
;                             for (int n = 0; n < 2; ++n) { const f32x4 hv = ((bs[mm][bj][n] - st[mm][0]) * st[mm][1]) * gv[bj][n] + bv[bj][n];
;                                 *(f32x4*)(ob + off0 + (unsigned)((ai * HALF + (2 * mh + mm) * 16) * 1024 + bj * HALF + n * 16) * 4u) = hv * DN_ALPHA + acc[ai][bj][2 * mh + mm][n]; }
;                     asm volatile("" : "+v"(off0), "+v"(soff0) :: "memory"); }
	v_sub_f32_e32 v163, v163, v184
	v_sub_f32_e32 v162, v162, v184
	v_sub_f32_e32 v165, v165, v184
	v_sub_f32_e32 v164, v164, v184
	v_pk_mul_f32 v[202:203], v[184:185], v[202:203] op_sel:[1,0]
	v_pk_mul_f32 v[192:193], v[184:185], v[192:193] op_sel:[1,0]
	v_pk_mul_f32 v[172:173], v[184:185], v[172:173] op_sel:[1,0]
	v_pk_mul_f32 v[170:171], v[184:185], v[170:171] op_sel:[1,0]
	v_pk_mul_f32 v[168:169], v[184:185], v[168:169] op_sel:[1,0]
	v_pk_mul_f32 v[166:167], v[184:185], v[166:167] op_sel:[1,0]
	v_pk_mul_f32 v[164:165], v[184:185], v[164:165] op_sel:[1,0]
	v_pk_mul_f32 v[162:163], v[184:185], v[162:163] op_sel:[1,0]
	v_pk_fma_f32 v[192:193], v[154:155], v[192:193], v[158:159]
	v_pk_fma_f32 v[202:203], v[156:157], v[202:203], v[160:161]
	v_pk_fma_f32 v[170:171], v[146:147], v[170:171], v[150:151]
	v_pk_fma_f32 v[172:173], v[148:149], v[172:173], v[152:153]
	v_pk_fma_f32 v[166:167], v[138:139], v[166:167], v[142:143]
	v_pk_fma_f32 v[168:169], v[140:141], v[168:169], v[144:145]
	v_pk_fma_f32 v[162:163], v[130:131], v[162:163], v[134:135]
	v_pk_fma_f32 v[164:165], v[132:133], v[164:165], v[136:137]
	v_pk_fma_f32 v[204:205], v[202:203], s[88:89], v[78:79] op_sel_hi:[1,0,1]
	v_pk_fma_f32 v[202:203], v[192:193], s[88:89], v[76:77] op_sel_hi:[1,0,1]
	v_pk_fma_f32 v[172:173], v[172:173], s[88:89], v[74:75] op_sel_hi:[1,0,1]
	v_pk_fma_f32 v[170:171], v[170:171], s[88:89], v[72:73] op_sel_hi:[1,0,1]
	v_pk_fma_f32 v[168:169], v[168:169], s[88:89], v[70:71] op_sel_hi:[1,0,1]
	v_pk_fma_f32 v[166:167], v[166:167], s[88:89], v[68:69] op_sel_hi:[1,0,1]
	v_pk_fma_f32 v[164:165], v[164:165], s[88:89], v[66:67] op_sel_hi:[1,0,1]
	v_pk_fma_f32 v[162:163], v[162:163], s[88:89], v[64:65] op_sel_hi:[1,0,1]
	global_store_dwordx4 v[186:187], v[202:205], off
	global_store_dwordx4 v[186:187], v[170:173], off offset:64
	global_store_dwordx4 v[186:187], v[166:169], off offset:512
	global_store_dwordx4 v[186:187], v[162:165], off offset:576
	global_load_dwordx2 v[210:211], v190, s[70:71] offset:1024
	v_lshl_add_u64 v[192:193], s[68:69], 0, v[182:183]
	v_add_co_u32_e32 v184, vcc, s24, v192
	s_nop 1
	v_addc_co_u32_e32 v185, vcc, 0, v193, vcc
	global_load_dwordx4 v[162:165], v[184:185], off nt
	global_load_dwordx4 v[166:169], v[184:185], off offset:64 nt
	global_load_dwordx4 v[170:173], v[184:185], off offset:512 nt
	s_nop 0
	global_load_dwordx4 v[184:187], v[184:185], off offset:576 nt
	s_nop 0
	global_load_dwordx2 v[238:239], v190, s[70:71] offset:1152
	v_add_co_u32_e32 v192, vcc, s25, v192
	s_waitcnt vmcnt(4)
	v_sub_f32_e32 v163, v163, v210
	v_addc_co_u32_e32 v193, vcc, 0, v193, vcc
	global_load_dwordx4 v[202:205], v[192:193], off nt
	global_load_dwordx4 v[206:209], v[192:193], off offset:64 nt
	global_load_dwordx4 v[230:233], v[192:193], off offset:512 nt
	global_load_dwordx4 v[234:237], v[192:193], off offset:576 nt
	v_sub_f32_e32 v162, v162, v210
	v_sub_f32_e32 v165, v165, v210
	v_sub_f32_e32 v164, v164, v210
	v_lshl_add_u64 v[192:193], s[66:67], 0, v[182:183]
	v_pk_mul_f32 v[164:165], v[210:211], v[164:165] op_sel:[1,0]
	v_pk_mul_f32 v[162:163], v[210:211], v[162:163] op_sel:[1,0]
	v_pk_fma_f32 v[164:165], v[156:157], v[164:165], v[160:161]
	v_pk_fma_f32 v[162:163], v[154:155], v[162:163], v[158:159]
	v_add_co_u32_e32 v240, vcc, s24, v192
	v_pk_fma_f32 v[164:165], v[164:165], s[88:89], v[62:63] op_sel_hi:[1,0,1]
	v_pk_fma_f32 v[162:163], v[162:163], s[88:89], v[60:61] op_sel_hi:[1,0,1]
	v_addc_co_u32_e32 v241, vcc, 0, v193, vcc
	global_store_dwordx4 v[240:241], v[162:165], off
	s_mov_b32 s24, 0xa0000
	s_waitcnt vmcnt(8)
	v_sub_f32_e32 v163, v167, v210
	v_sub_f32_e32 v162, v166, v210
	v_sub_f32_e32 v165, v169, v210
	v_sub_f32_e32 v164, v168, v210
	v_pk_mul_f32 v[164:165], v[210:211], v[164:165] op_sel:[1,0]
	v_pk_mul_f32 v[162:163], v[210:211], v[162:163] op_sel:[1,0]
	v_pk_fma_f32 v[164:165], v[148:149], v[164:165], v[152:153]
	v_pk_fma_f32 v[162:163], v[146:147], v[162:163], v[150:151]
	v_pk_fma_f32 v[164:165], v[164:165], s[88:89], v[58:59] op_sel_hi:[1,0,1]
	v_pk_fma_f32 v[162:163], v[162:163], s[88:89], v[56:57] op_sel_hi:[1,0,1]
	global_store_dwordx4 v[240:241], v[162:165], off offset:64
	v_add_co_u32_e32 v166, vcc, s25, v192
	s_waitcnt vmcnt(8)
	v_sub_f32_e32 v163, v171, v210
	v_sub_f32_e32 v162, v170, v210
	v_sub_f32_e32 v165, v173, v210
	v_sub_f32_e32 v164, v172, v210
	v_pk_mul_f32 v[164:165], v[210:211], v[164:165] op_sel:[1,0]
	v_pk_mul_f32 v[162:163], v[210:211], v[162:163] op_sel:[1,0]
	v_pk_fma_f32 v[164:165], v[140:141], v[164:165], v[144:145]
	v_pk_fma_f32 v[162:163], v[138:139], v[162:163], v[142:143]
	v_pk_fma_f32 v[164:165], v[164:165], s[88:89], v[54:55] op_sel_hi:[1,0,1]
	v_pk_fma_f32 v[162:163], v[162:163], s[88:89], v[52:53] op_sel_hi:[1,0,1]
	global_store_dwordx4 v[240:241], v[162:165], off offset:512
	v_addc_co_u32_e32 v167, vcc, 0, v193, vcc
	s_waitcnt vmcnt(8)
	v_sub_f32_e32 v163, v185, v210
	v_sub_f32_e32 v162, v184, v210
	v_sub_f32_e32 v165, v187, v210
	v_sub_f32_e32 v164, v186, v210
	v_pk_mul_f32 v[164:165], v[210:211], v[164:165] op_sel:[1,0]
	v_pk_mul_f32 v[162:163], v[210:211], v[162:163] op_sel:[1,0]
	v_pk_fma_f32 v[164:165], v[132:133], v[164:165], v[136:137]
	v_pk_fma_f32 v[162:163], v[130:131], v[162:163], v[134:135]
	v_pk_fma_f32 v[164:165], v[164:165], s[88:89], v[50:51] op_sel_hi:[1,0,1]
	v_pk_fma_f32 v[162:163], v[162:163], s[88:89], v[48:49] op_sel_hi:[1,0,1]
	global_store_dwordx4 v[240:241], v[162:165], off offset:576
	s_mov_b32 s25, 0xb0000
	s_waitcnt vmcnt(7)
;     __device__ __forceinline__ void operator()(const f32x4 (&acc)[2][2][4][2], const Unit& u, int wr, int wc, int fr, int fq) const {
;     ...
;             for (int ai = 0; ai < 2; ++ai)
; #pragma unroll
;                 for (int mh = 0; mh < 2; ++mh) {
;                     f32x4 bs[2][2][2]; f32x2_t st[2];
; #pragma unroll
;                     for (int mm = 0; mm < 2; ++mm) { st[mm] = *(const f32x2_t*)(sp + soff0 + (unsigned)(ai * HALF + (2 * mh + mm) * 16) * 8u);
; #pragma unroll
;                         for (int bj = 0; bj < 2; ++bj)
; #pragma unroll
;                             for (int n = 0; n < 2; ++n) bs[mm][bj][n] = *(const f32x4*)(bb + off0 + (unsigned)((ai * HALF + (2 * mh + mm) * 16) * 1024 + bj * HALF + n * 16) * 4u); }
; #pragma unroll
;                     for (int mm = 0; mm < 2; ++mm)
; #pragma unroll
;                         for (int bj = 0; bj < 2; ++bj)
; #pragma unroll
;                             for (int n = 0; n < 2; ++n) { const f32x4 hv = ((bs[mm][bj][n] - st[mm][0]) * st[mm][1]) * gv[bj][n] + bv[bj][n];
;                                 *(f32x4*)(ob + off0 + (unsigned)((ai * HALF + (2 * mh + mm) * 16) * 1024 + bj * HALF + n * 16) * 4u) = hv * DN_ALPHA + acc[ai][bj][2 * mh + mm][n]; }
;                     asm volatile("" : "+v"(off0), "+v"(soff0) :: "memory"); }
	v_sub_f32_e32 v163, v203, v238
	v_sub_f32_e32 v162, v202, v238
	v_sub_f32_e32 v165, v205, v238
	v_sub_f32_e32 v164, v204, v238
	v_pk_mul_f32 v[164:165], v[238:239], v[164:165] op_sel:[1,0]
	v_pk_mul_f32 v[162:163], v[238:239], v[162:163] op_sel:[1,0]
	v_pk_fma_f32 v[164:165], v[156:157], v[164:165], v[160:161]
	v_pk_fma_f32 v[162:163], v[154:155], v[162:163], v[158:159]
	v_pk_fma_f32 v[164:165], v[164:165], s[88:89], v[46:47] op_sel_hi:[1,0,1]
	v_pk_fma_f32 v[162:163], v[162:163], s[88:89], v[44:45] op_sel_hi:[1,0,1]
	global_store_dwordx4 v[166:167], v[162:165], off
	s_waitcnt vmcnt(7)
	s_nop 0
	v_sub_f32_e32 v163, v207, v238
	v_sub_f32_e32 v162, v206, v238
	v_sub_f32_e32 v165, v209, v238
	v_sub_f32_e32 v164, v208, v238
	v_pk_mul_f32 v[164:165], v[238:239], v[164:165] op_sel:[1,0]
	v_pk_mul_f32 v[162:163], v[238:239], v[162:163] op_sel:[1,0]
	v_pk_fma_f32 v[164:165], v[148:149], v[164:165], v[152:153]
	v_pk_fma_f32 v[162:163], v[146:147], v[162:163], v[150:151]
	v_pk_fma_f32 v[164:165], v[164:165], s[88:89], v[42:43] op_sel_hi:[1,0,1]
	v_pk_fma_f32 v[162:163], v[162:163], s[88:89], v[40:41] op_sel_hi:[1,0,1]
	global_store_dwordx4 v[166:167], v[162:165], off offset:64
	s_waitcnt vmcnt(7)
	s_nop 0
	v_sub_f32_e32 v163, v231, v238
	v_sub_f32_e32 v162, v230, v238
	v_sub_f32_e32 v165, v233, v238
	v_sub_f32_e32 v164, v232, v238
	v_pk_mul_f32 v[164:165], v[238:239], v[164:165] op_sel:[1,0]
	v_pk_mul_f32 v[162:163], v[238:239], v[162:163] op_sel:[1,0]
	v_pk_fma_f32 v[164:165], v[140:141], v[164:165], v[144:145]
	v_pk_fma_f32 v[162:163], v[138:139], v[162:163], v[142:143]
	v_pk_fma_f32 v[164:165], v[164:165], s[88:89], v[38:39] op_sel_hi:[1,0,1]
	v_pk_fma_f32 v[162:163], v[162:163], s[88:89], v[36:37] op_sel_hi:[1,0,1]
	global_store_dwordx4 v[166:167], v[162:165], off offset:512
	s_waitcnt vmcnt(7)
	s_nop 0
	v_sub_f32_e32 v163, v235, v238
	v_sub_f32_e32 v162, v234, v238
	v_sub_f32_e32 v165, v237, v238
	v_sub_f32_e32 v164, v236, v238
	v_pk_mul_f32 v[164:165], v[238:239], v[164:165] op_sel:[1,0]
	v_pk_mul_f32 v[162:163], v[238:239], v[162:163] op_sel:[1,0]
	v_pk_fma_f32 v[164:165], v[132:133], v[164:165], v[136:137]
	v_pk_fma_f32 v[162:163], v[130:131], v[162:163], v[134:135]
	v_pk_fma_f32 v[164:165], v[164:165], s[88:89], v[30:31] op_sel_hi:[1,0,1]
	v_pk_fma_f32 v[162:163], v[162:163], s[88:89], v[28:29] op_sel_hi:[1,0,1]
	global_store_dwordx4 v[166:167], v[162:165], off offset:576
	global_load_dwordx2 v[210:211], v190, s[70:71] offset:1280
	v_lshl_add_u64 v[192:193], s[68:69], 0, v[182:183]
	v_add_co_u32_e32 v184, vcc, s24, v192
	s_nop 1
	v_addc_co_u32_e32 v185, vcc, 0, v193, vcc
	global_load_dwordx4 v[162:165], v[184:185], off nt
	global_load_dwordx4 v[166:169], v[184:185], off offset:64 nt
	global_load_dwordx4 v[170:173], v[184:185], off offset:512 nt
	s_nop 0
	global_load_dwordx4 v[184:187], v[184:185], off offset:576 nt
	s_nop 0
	global_load_dwordx2 v[238:239], v190, s[70:71] offset:1408
	v_add_co_u32_e32 v192, vcc, s25, v192
	s_waitcnt vmcnt(4)
	v_sub_f32_e32 v163, v163, v210
	v_addc_co_u32_e32 v193, vcc, 0, v193, vcc
	global_load_dwordx4 v[202:205], v[192:193], off nt
	global_load_dwordx4 v[206:209], v[192:193], off offset:64 nt
	global_load_dwordx4 v[230:233], v[192:193], off offset:512 nt
	global_load_dwordx4 v[234:237], v[192:193], off offset:576 nt
	v_sub_f32_e32 v162, v162, v210
	v_sub_f32_e32 v165, v165, v210
	v_sub_f32_e32 v164, v164, v210
	v_lshl_add_u64 v[192:193], s[66:67], 0, v[182:183]
	v_pk_mul_f32 v[164:165], v[210:211], v[164:165] op_sel:[1,0]
	v_pk_mul_f32 v[162:163], v[210:211], v[162:163] op_sel:[1,0]
	v_pk_fma_f32 v[164:165], v[156:157], v[164:165], v[160:161]
	v_pk_fma_f32 v[162:163], v[154:155], v[162:163], v[158:159]
	v_add_co_u32_e32 v240, vcc, s24, v192
	v_pk_fma_f32 v[164:165], v[164:165], s[88:89], v[34:35] op_sel_hi:[1,0,1]
	v_pk_fma_f32 v[162:163], v[162:163], s[88:89], v[32:33] op_sel_hi:[1,0,1]
	v_addc_co_u32_e32 v241, vcc, 0, v193, vcc
	global_store_dwordx4 v[240:241], v[162:165], off
	s_waitcnt vmcnt(8)
	s_nop 0
	v_sub_f32_e32 v163, v167, v210
	v_sub_f32_e32 v162, v166, v210
	v_sub_f32_e32 v165, v169, v210
	v_sub_f32_e32 v164, v168, v210
	v_pk_mul_f32 v[164:165], v[210:211], v[164:165] op_sel:[1,0]
	v_pk_mul_f32 v[162:163], v[210:211], v[162:163] op_sel:[1,0]
	v_pk_fma_f32 v[164:165], v[148:149], v[164:165], v[152:153]
	v_pk_fma_f32 v[162:163], v[146:147], v[162:163], v[150:151]
	v_pk_fma_f32 v[164:165], v[164:165], s[88:89], v[26:27] op_sel_hi:[1,0,1]
	v_pk_fma_f32 v[162:163], v[162:163], s[88:89], v[24:25] op_sel_hi:[1,0,1]
	global_store_dwordx4 v[240:241], v[162:165], off offset:64
	s_waitcnt vmcnt(8)
	s_nop 0
	v_sub_f32_e32 v163, v171, v210
	v_sub_f32_e32 v162, v170, v210
	v_sub_f32_e32 v165, v173, v210
	v_sub_f32_e32 v164, v172, v210
	v_pk_mul_f32 v[164:165], v[210:211], v[164:165] op_sel:[1,0]
	v_pk_mul_f32 v[162:163], v[210:211], v[162:163] op_sel:[1,0]
	v_pk_fma_f32 v[164:165], v[140:141], v[164:165], v[144:145]
	v_pk_fma_f32 v[162:163], v[138:139], v[162:163], v[142:143]
	v_pk_fma_f32 v[164:165], v[164:165], s[88:89], v[22:23] op_sel_hi:[1,0,1]
	v_pk_fma_f32 v[162:163], v[162:163], s[88:89], v[20:21] op_sel_hi:[1,0,1]
	global_store_dwordx4 v[240:241], v[162:165], off offset:512
	s_waitcnt vmcnt(8)
	s_nop 0
	v_sub_f32_e32 v163, v185, v210
	v_sub_f32_e32 v162, v184, v210
	v_sub_f32_e32 v165, v187, v210
	v_sub_f32_e32 v164, v186, v210
	v_pk_mul_f32 v[164:165], v[210:211], v[164:165] op_sel:[1,0]
	v_pk_mul_f32 v[162:163], v[210:211], v[162:163] op_sel:[1,0]
	v_pk_fma_f32 v[164:165], v[132:133], v[164:165], v[136:137]
	v_pk_fma_f32 v[162:163], v[130:131], v[162:163], v[134:135]
	v_pk_fma_f32 v[164:165], v[164:165], s[88:89], v[18:19] op_sel_hi:[1,0,1]
	v_pk_fma_f32 v[162:163], v[162:163], s[88:89], v[16:17] op_sel_hi:[1,0,1]
	global_store_dwordx4 v[240:241], v[162:165], off offset:576
	s_waitcnt vmcnt(7)
;     __device__ __forceinline__ void operator()(const f32x4 (&acc)[2][2][4][2], const Unit& u, int wr, int wc, int fr, int fq) const {
;     ...
;         if (stats == nullptr) {
; #pragma unroll
;             for (int ai = 0; ai < 2; ++ai) {
;                 f32x4 bs[4][2][2];
; #pragma unroll
;                 for (int m = 0; m < 4; ++m)
; #pragma unroll
;                     for (int bj = 0; bj < 2; ++bj)
; #pragma unroll
;                         for (int n = 0; n < 2; ++n) bs[m][bj][n] = *(const f32x4*)(bb + off0 + (unsigned)((ai * HALF + m * 16) * 1024 + bj * HALF + n * 16) * 4u);
; #pragma unroll
;                 for (int m = 0; m < 4; ++m)
; #pragma unroll
;                     for (int bj = 0; bj < 2; ++bj)
; #pragma unroll
;                         for (int n = 0; n < 2; ++n) *(f32x4*)(ob + off0 + (unsigned)((ai * HALF + m * 16) * 1024 + bj * HALF + n * 16) * 4u) = bs[m][bj][n] * DN_ALPHA + acc[ai][bj][m][n];
;                 asm volatile("" : "+v"(off0) :: "memory"); }
;     ...
;             for (int ai = 0; ai < 2; ++ai)
; #pragma unroll
;                 for (int mh = 0; mh < 2; ++mh) {
;                     f32x4 bs[2][2][2]; f32x2_t st[2];
; #pragma unroll
;                     for (int mm = 0; mm < 2; ++mm) { st[mm] = *(const f32x2_t*)(sp + soff0 + (unsigned)(ai * HALF + (2 * mh + mm) * 16) * 8u);
; #pragma unroll
;                         for (int bj = 0; bj < 2; ++bj)
; #pragma unroll
;                             for (int n = 0; n < 2; ++n) bs[mm][bj][n] = *(const f32x4*)(bb + off0 + (unsigned)((ai * HALF + (2 * mh + mm) * 16) * 1024 + bj * HALF + n * 16) * 4u); }
; #pragma unroll
;                     for (int mm = 0; mm < 2; ++mm)
; #pragma unroll
;                         for (int bj = 0; bj < 2; ++bj)
; #pragma unroll
;                             for (int n = 0; n < 2; ++n) { const f32x4 hv = ((bs[mm][bj][n] - st[mm][0]) * st[mm][1]) * gv[bj][n] + bv[bj][n];
;                                 *(f32x4*)(ob + off0 + (unsigned)((ai * HALF + (2 * mh + mm) * 16) * 1024 + bj * HALF + n * 16) * 4u) = hv * DN_ALPHA + acc[ai][bj][2 * mh + mm][n]; }
;                     asm volatile("" : "+v"(off0), "+v"(soff0) :: "memory"); }
	s_nop 0
	v_sub_f32_e32 v163, v203, v238
	v_sub_f32_e32 v162, v202, v238
	v_sub_f32_e32 v165, v205, v238
	v_sub_f32_e32 v164, v204, v238
	v_pk_mul_f32 v[164:165], v[238:239], v[164:165] op_sel:[1,0]
	v_pk_mul_f32 v[162:163], v[238:239], v[162:163] op_sel:[1,0]
	v_pk_fma_f32 v[156:157], v[156:157], v[164:165], v[160:161]
	v_pk_fma_f32 v[154:155], v[154:155], v[162:163], v[158:159]
	v_add_co_u32_e32 v158, vcc, s25, v192
	v_pk_fma_f32 v[156:157], v[156:157], s[88:89], v[14:15] op_sel_hi:[1,0,1]
	v_pk_fma_f32 v[154:155], v[154:155], s[88:89], v[12:13] op_sel_hi:[1,0,1]
	v_addc_co_u32_e32 v159, vcc, 0, v193, vcc
	global_store_dwordx4 v[158:159], v[154:157], off
	s_waitcnt vmcnt(7)
	s_nop 0
	v_sub_f32_e32 v155, v207, v238
	v_sub_f32_e32 v154, v206, v238
	v_sub_f32_e32 v157, v209, v238
	v_sub_f32_e32 v156, v208, v238
	v_pk_mul_f32 v[156:157], v[238:239], v[156:157] op_sel:[1,0]
	v_pk_mul_f32 v[154:155], v[238:239], v[154:155] op_sel:[1,0]
	v_pk_fma_f32 v[148:149], v[148:149], v[156:157], v[152:153]
	v_pk_fma_f32 v[146:147], v[146:147], v[154:155], v[150:151]
	v_pk_fma_f32 v[148:149], v[148:149], s[88:89], v[10:11] op_sel_hi:[1,0,1]
	v_pk_fma_f32 v[146:147], v[146:147], s[88:89], v[8:9] op_sel_hi:[1,0,1]
	global_store_dwordx4 v[158:159], v[146:149], off offset:64
	s_waitcnt vmcnt(7)
	s_nop 0
	v_sub_f32_e32 v147, v231, v238
	v_sub_f32_e32 v146, v230, v238
	v_sub_f32_e32 v149, v233, v238
	v_sub_f32_e32 v148, v232, v238
	v_pk_mul_f32 v[148:149], v[238:239], v[148:149] op_sel:[1,0]
	v_pk_mul_f32 v[146:147], v[238:239], v[146:147] op_sel:[1,0]
	v_pk_fma_f32 v[140:141], v[140:141], v[148:149], v[144:145]
	v_pk_fma_f32 v[138:139], v[138:139], v[146:147], v[142:143]
	v_pk_fma_f32 v[140:141], v[140:141], s[88:89], v[6:7] op_sel_hi:[1,0,1]
	v_pk_fma_f32 v[138:139], v[138:139], s[88:89], v[4:5] op_sel_hi:[1,0,1]
	global_store_dwordx4 v[158:159], v[138:141], off offset:512
	s_waitcnt vmcnt(7)
	s_nop 0
	v_sub_f32_e32 v139, v235, v238
	v_sub_f32_e32 v138, v234, v238
	v_sub_f32_e32 v141, v237, v238
	v_sub_f32_e32 v140, v236, v238
	v_pk_mul_f32 v[140:141], v[238:239], v[140:141] op_sel:[1,0]
	v_pk_mul_f32 v[138:139], v[238:239], v[138:139] op_sel:[1,0]
	v_pk_fma_f32 v[132:133], v[132:133], v[140:141], v[136:137]
	v_pk_fma_f32 v[130:131], v[130:131], v[138:139], v[134:135]
	v_pk_fma_f32 v[132:133], v[132:133], s[88:89], v[2:3] op_sel_hi:[1,0,1]
	v_pk_fma_f32 v[130:131], v[130:131], s[88:89], v[0:1] op_sel_hi:[1,0,1]
	global_store_dwordx4 v[158:159], v[130:133], off offset:576
.LBB0_445:
	s_andn2_b64 vcc, exec, s[72:73]
	v_readlane_b32 s78, v252, 44
	v_readlane_b32 s79, v252, 45
	s_cbranch_vccnz .LBB0_447
	v_lshl_add_u64 v[130:131], s[68:69], 0, v[96:97]
	global_load_dwordx4 v[144:147], v96, s[68:69]
	global_load_dwordx4 v[148:151], v96, s[68:69] offset:64
	global_load_dwordx4 v[152:155], v96, s[68:69] offset:512
	global_load_dwordx4 v[156:159], v96, s[68:69] offset:576
	v_add_co_u32_e32 v132, vcc, 0x10000, v130
	v_lshl_add_u64 v[142:143], s[66:67], 0, v[96:97]
	s_nop 0
	v_addc_co_u32_e32 v133, vcc, 0, v131, vcc
	global_load_dwordx4 v[160:163], v[132:133], off nt
	global_load_dwordx4 v[164:167], v[132:133], off offset:64 nt
	global_load_dwordx4 v[168:171], v[132:133], off offset:512 nt
	global_load_dwordx4 v[182:185], v[132:133], off offset:576 nt
	v_add_co_u32_e32 v132, vcc, 0x20000, v130
	s_mov_b32 s24, 0x10000
	s_nop 0
	v_addc_co_u32_e32 v133, vcc, 0, v131, vcc
	global_load_dwordx4 v[190:193], v[132:133], off nt
	global_load_dwordx4 v[202:205], v[132:133], off offset:64 nt
	global_load_dwordx4 v[206:209], v[132:133], off offset:512 nt
	global_load_dwordx4 v[230:233], v[132:133], off offset:576 nt
	v_add_co_u32_e32 v130, vcc, 0x30000, v130
	s_mov_b32 s25, 0x90000
	s_nop 0
	v_addc_co_u32_e32 v131, vcc, 0, v131, vcc
	global_load_dwordx4 v[234:237], v[130:131], off nt
	global_load_dwordx4 v[138:141], v[130:131], off offset:64 nt
	global_load_dwordx4 v[134:137], v[130:131], off offset:512 nt
	s_nop 0
	global_load_dwordx4 v[130:133], v[130:131], off offset:576 nt
	s_waitcnt vmcnt(0)
	v_pk_fma_f32 v[126:127], v[144:145], s[88:89], v[126:127] op_sel_hi:[1,0,1]
	v_pk_fma_f32 v[128:129], v[146:147], s[88:89], v[128:129] op_sel_hi:[1,0,1]
	v_pk_fma_f32 v[122:123], v[148:149], s[88:89], v[122:123] op_sel_hi:[1,0,1]
	v_pk_fma_f32 v[114:115], v[156:157], s[88:89], v[114:115] op_sel_hi:[1,0,1]
	v_pk_fma_f32 v[116:117], v[158:159], s[88:89], v[116:117] op_sel_hi:[1,0,1]
	global_store_dwordx4 v96, v[114:117], s[66:67] offset:576
	v_pk_fma_f32 v[124:125], v[150:151], s[88:89], v[124:125] op_sel_hi:[1,0,1]
	v_pk_fma_f32 v[118:119], v[152:153], s[88:89], v[118:119] op_sel_hi:[1,0,1]
	v_add_co_u32_e32 v114, vcc, s24, v142
	v_pk_fma_f32 v[100:101], v[184:185], s[88:89], v[100:101] op_sel_hi:[1,0,1]
	s_nop 0
	v_addc_co_u32_e32 v115, vcc, 0, v143, vcc
	v_pk_fma_f32 v[98:99], v[182:183], s[88:89], v[98:99] op_sel_hi:[1,0,1]
	s_mov_b32 s24, 0x20000
	global_store_dwordx4 v[114:115], v[98:101], off offset:576
	v_pk_fma_f32 v[82:83], v[232:233], s[88:89], v[82:83] op_sel_hi:[1,0,1]
	v_pk_fma_f32 v[80:81], v[230:231], s[88:89], v[80:81] op_sel_hi:[1,0,1]
	v_add_co_u32_e32 v98, vcc, s24, v142
	s_mov_b32 s24, 0x30000
	s_nop 0
	v_addc_co_u32_e32 v99, vcc, 0, v143, vcc
	global_store_dwordx4 v[98:99], v[80:83], off offset:576
	v_pk_fma_f32 v[120:121], v[154:155], s[88:89], v[120:121] op_sel_hi:[1,0,1]
	v_pk_fma_f32 v[112:113], v[162:163], s[88:89], v[112:113] op_sel_hi:[1,0,1]
	v_add_co_u32_e32 v80, vcc, s24, v142
	v_pk_fma_f32 v[110:111], v[160:161], s[88:89], v[110:111] op_sel_hi:[1,0,1]
	v_pk_fma_f32 v[108:109], v[166:167], s[88:89], v[108:109] op_sel_hi:[1,0,1]
;     __device__ __forceinline__ void operator()(const f32x4 (&acc)[2][2][4][2], const Unit& u, int wr, int wc, int fr, int fq) const {
;     ...
;         if (stats == nullptr) {
; #pragma unroll
;             for (int ai = 0; ai < 2; ++ai) {
;                 f32x4 bs[4][2][2];
; #pragma unroll
;                 for (int m = 0; m < 4; ++m)
; #pragma unroll
;                     for (int bj = 0; bj < 2; ++bj)
; #pragma unroll
;                         for (int n = 0; n < 2; ++n) bs[m][bj][n] = *(const f32x4*)(bb + off0 + (unsigned)((ai * HALF + m * 16) * 1024 + bj * HALF + n * 16) * 4u);
; #pragma unroll
;                 for (int m = 0; m < 4; ++m)
; #pragma unroll
;                     for (int bj = 0; bj < 2; ++bj)
; #pragma unroll
;                         for (int n = 0; n < 2; ++n) *(f32x4*)(ob + off0 + (unsigned)((ai * HALF + m * 16) * 1024 + bj * HALF + n * 16) * 4u) = bs[m][bj][n] * DN_ALPHA + acc[ai][bj][m][n];
;                 asm volatile("" : "+v"(off0) :: "memory"); }
	v_pk_fma_f32 v[106:107], v[164:165], s[88:89], v[106:107] op_sel_hi:[1,0,1]
	v_pk_fma_f32 v[104:105], v[170:171], s[88:89], v[104:105] op_sel_hi:[1,0,1]
	v_pk_fma_f32 v[102:103], v[168:169], s[88:89], v[102:103] op_sel_hi:[1,0,1]
	v_pk_fma_f32 v[94:95], v[192:193], s[88:89], v[94:95] op_sel_hi:[1,0,1]
	v_pk_fma_f32 v[92:93], v[190:191], s[88:89], v[92:93] op_sel_hi:[1,0,1]
	v_pk_fma_f32 v[90:91], v[204:205], s[88:89], v[90:91] op_sel_hi:[1,0,1]
	v_pk_fma_f32 v[88:89], v[202:203], s[88:89], v[88:89] op_sel_hi:[1,0,1]
	v_pk_fma_f32 v[86:87], v[208:209], s[88:89], v[86:87] op_sel_hi:[1,0,1]
	v_pk_fma_f32 v[84:85], v[206:207], s[88:89], v[84:85] op_sel_hi:[1,0,1]
	v_pk_fma_f32 v[78:79], v[236:237], s[88:89], v[78:79] op_sel_hi:[1,0,1]
	v_pk_fma_f32 v[76:77], v[234:235], s[88:89], v[76:77] op_sel_hi:[1,0,1]
	v_addc_co_u32_e32 v81, vcc, 0, v143, vcc
	v_pk_fma_f32 v[74:75], v[140:141], s[88:89], v[74:75] op_sel_hi:[1,0,1]
	v_pk_fma_f32 v[72:73], v[138:139], s[88:89], v[72:73] op_sel_hi:[1,0,1]
	v_pk_fma_f32 v[70:71], v[136:137], s[88:89], v[70:71] op_sel_hi:[1,0,1]
	v_pk_fma_f32 v[68:69], v[134:135], s[88:89], v[68:69] op_sel_hi:[1,0,1]
	v_pk_fma_f32 v[66:67], v[132:133], s[88:89], v[66:67] op_sel_hi:[1,0,1]
	v_pk_fma_f32 v[64:65], v[130:131], s[88:89], v[64:65] op_sel_hi:[1,0,1]
	global_store_dwordx4 v96, v[126:129], s[66:67]
	global_store_dwordx4 v96, v[122:125], s[66:67] offset:64
	global_store_dwordx4 v96, v[118:121], s[66:67] offset:512
	global_store_dwordx4 v[114:115], v[110:113], off
	global_store_dwordx4 v[114:115], v[106:109], off offset:64
	global_store_dwordx4 v[114:115], v[102:105], off offset:512
	global_store_dwordx4 v[98:99], v[92:95], off
	global_store_dwordx4 v[98:99], v[88:91], off offset:64
	global_store_dwordx4 v[98:99], v[84:87], off offset:512
	global_store_dwordx4 v[80:81], v[76:79], off
	global_store_dwordx4 v[80:81], v[72:75], off offset:64
	global_store_dwordx4 v[80:81], v[68:71], off offset:512
	global_store_dwordx4 v[80:81], v[64:67], off offset:576
	s_mov_b32 s24, 0x80000
	v_lshl_add_u64 v[92:93], s[66:67], 0, v[96:97]
	v_lshl_add_u64 v[64:65], s[68:69], 0, v[96:97]
	v_add_co_u32_e32 v66, vcc, s24, v64
	s_mov_b32 s68, 0xa0000
	s_nop 0
	v_addc_co_u32_e32 v67, vcc, 0, v65, vcc
	global_load_dwordx4 v[98:101], v[66:67], off nt
	global_load_dwordx4 v[102:105], v[66:67], off offset:64 nt
	global_load_dwordx4 v[106:109], v[66:67], off offset:512 nt
	global_load_dwordx4 v[110:113], v[66:67], off offset:576 nt
	v_add_co_u32_e32 v66, vcc, s25, v64
	s_mov_b32 s69, 0xb0000
	s_nop 0
	v_addc_co_u32_e32 v67, vcc, 0, v65, vcc
	global_load_dwordx4 v[114:117], v[66:67], off nt
	global_load_dwordx4 v[118:121], v[66:67], off offset:64 nt
	global_load_dwordx4 v[122:125], v[66:67], off offset:512 nt
	global_load_dwordx4 v[126:129], v[66:67], off offset:576 nt
	v_add_co_u32_e32 v66, vcc, s68, v64
	s_waitcnt vmcnt(7)
	v_pk_fma_f32 v[62:63], v[100:101], s[88:89], v[62:63] op_sel_hi:[1,0,1]
	v_addc_co_u32_e32 v67, vcc, 0, v65, vcc
	global_load_dwordx4 v[130:133], v[66:67], off nt
	global_load_dwordx4 v[88:91], v[66:67], off offset:64 nt
	global_load_dwordx4 v[84:87], v[66:67], off offset:512 nt
	global_load_dwordx4 v[80:83], v[66:67], off offset:576 nt
	v_add_co_u32_e32 v64, vcc, s69, v64
	s_waitcnt vmcnt(8)
;     __device__ __forceinline__ void operator()(const f32x4 (&acc)[2][2][4][2], const Unit& u, int wr, int wc, int fr, int fq) const {
;     ...
;         if (stats == nullptr) {
; #pragma unroll
;             for (int ai = 0; ai < 2; ++ai) {
;                 f32x4 bs[4][2][2];
; #pragma unroll
;                 for (int m = 0; m < 4; ++m)
; #pragma unroll
;                     for (int bj = 0; bj < 2; ++bj)
; #pragma unroll
;                         for (int n = 0; n < 2; ++n) bs[m][bj][n] = *(const f32x4*)(bb + off0 + (unsigned)((ai * HALF + m * 16) * 1024 + bj * HALF + n * 16) * 4u);
; #pragma unroll
;                 for (int m = 0; m < 4; ++m)
; #pragma unroll
;                     for (int bj = 0; bj < 2; ++bj)
; #pragma unroll
;                         for (int n = 0; n < 2; ++n) *(f32x4*)(ob + off0 + (unsigned)((ai * HALF + m * 16) * 1024 + bj * HALF + n * 16) * 4u) = bs[m][bj][n] * DN_ALPHA + acc[ai][bj][m][n];
;                 asm volatile("" : "+v"(off0) :: "memory"); }
	v_pk_fma_f32 v[50:51], v[112:113], s[88:89], v[50:51] op_sel_hi:[1,0,1]
	v_addc_co_u32_e32 v65, vcc, 0, v65, vcc
	global_load_dwordx4 v[76:79], v[64:65], off nt
	global_load_dwordx4 v[72:75], v[64:65], off offset:64 nt
	global_load_dwordx4 v[68:71], v[64:65], off offset:512 nt
	s_nop 0
	global_load_dwordx4 v[64:67], v[64:65], off offset:576 nt
	v_add_co_u32_e32 v94, vcc, s24, v92
	v_pk_fma_f32 v[48:49], v[110:111], s[88:89], v[48:49] op_sel_hi:[1,0,1]
	s_nop 0
	v_addc_co_u32_e32 v95, vcc, 0, v93, vcc
	global_store_dwordx4 v[94:95], v[48:51], off offset:576
	s_waitcnt vmcnt(9)
	v_pk_fma_f32 v[30:31], v[128:129], s[88:89], v[30:31] op_sel_hi:[1,0,1]
	v_pk_fma_f32 v[28:29], v[126:127], s[88:89], v[28:29] op_sel_hi:[1,0,1]
	v_add_co_u32_e32 v48, vcc, s25, v92
	v_pk_fma_f32 v[60:61], v[98:99], s[88:89], v[60:61] op_sel_hi:[1,0,1]
	s_nop 0
	v_addc_co_u32_e32 v49, vcc, 0, v93, vcc
	global_store_dwordx4 v[48:49], v[28:31], off offset:576
	v_pk_fma_f32 v[58:59], v[104:105], s[88:89], v[58:59] op_sel_hi:[1,0,1]
	v_pk_fma_f32 v[56:57], v[102:103], s[88:89], v[56:57] op_sel_hi:[1,0,1]
	v_pk_fma_f32 v[54:55], v[108:109], s[88:89], v[54:55] op_sel_hi:[1,0,1]
	v_pk_fma_f32 v[52:53], v[106:107], s[88:89], v[52:53] op_sel_hi:[1,0,1]
	v_pk_fma_f32 v[46:47], v[116:117], s[88:89], v[46:47] op_sel_hi:[1,0,1]
	v_pk_fma_f32 v[44:45], v[114:115], s[88:89], v[44:45] op_sel_hi:[1,0,1]
	v_pk_fma_f32 v[42:43], v[120:121], s[88:89], v[42:43] op_sel_hi:[1,0,1]
	v_pk_fma_f32 v[40:41], v[118:119], s[88:89], v[40:41] op_sel_hi:[1,0,1]
	v_pk_fma_f32 v[38:39], v[124:125], s[88:89], v[38:39] op_sel_hi:[1,0,1]
	v_pk_fma_f32 v[36:37], v[122:123], s[88:89], v[36:37] op_sel_hi:[1,0,1]
	global_store_dwordx4 v[94:95], v[60:63], off
	global_store_dwordx4 v[94:95], v[56:59], off offset:64
	global_store_dwordx4 v[94:95], v[52:55], off offset:512
	global_store_dwordx4 v[48:49], v[44:47], off
	global_store_dwordx4 v[48:49], v[40:43], off offset:64
	global_store_dwordx4 v[48:49], v[36:39], off offset:512
	s_waitcnt vmcnt(15)
	v_pk_fma_f32 v[28:29], v[130:131], s[88:89], v[32:33] op_sel_hi:[1,0,1]
	v_add_co_u32_e32 v32, vcc, s68, v92
	s_waitcnt vmcnt(12)
	v_pk_fma_f32 v[18:19], v[82:83], s[88:89], v[18:19] op_sel_hi:[1,0,1]
	v_addc_co_u32_e32 v33, vcc, 0, v93, vcc
	v_pk_fma_f32 v[16:17], v[80:81], s[88:89], v[16:17] op_sel_hi:[1,0,1]
	global_store_dwordx4 v[32:33], v[16:19], off offset:576
	v_pk_fma_f32 v[30:31], v[132:133], s[88:89], v[34:35] op_sel_hi:[1,0,1]
	v_pk_fma_f32 v[26:27], v[90:91], s[88:89], v[26:27] op_sel_hi:[1,0,1]
	v_add_co_u32_e32 v16, vcc, s69, v92
	v_pk_fma_f32 v[24:25], v[88:89], s[88:89], v[24:25] op_sel_hi:[1,0,1]
	v_pk_fma_f32 v[22:23], v[86:87], s[88:89], v[22:23] op_sel_hi:[1,0,1]
	v_pk_fma_f32 v[20:21], v[84:85], s[88:89], v[20:21] op_sel_hi:[1,0,1]
	s_waitcnt vmcnt(12)
	v_pk_fma_f32 v[14:15], v[78:79], s[88:89], v[14:15] op_sel_hi:[1,0,1]
	v_pk_fma_f32 v[12:13], v[76:77], s[88:89], v[12:13] op_sel_hi:[1,0,1]
	v_addc_co_u32_e32 v17, vcc, 0, v93, vcc
	s_waitcnt vmcnt(11)
	v_pk_fma_f32 v[10:11], v[74:75], s[88:89], v[10:11] op_sel_hi:[1,0,1]
	v_pk_fma_f32 v[8:9], v[72:73], s[88:89], v[8:9] op_sel_hi:[1,0,1]
	s_waitcnt vmcnt(10)
	v_pk_fma_f32 v[6:7], v[70:71], s[88:89], v[6:7] op_sel_hi:[1,0,1]
	v_pk_fma_f32 v[4:5], v[68:69], s[88:89], v[4:5] op_sel_hi:[1,0,1]
	s_waitcnt vmcnt(9)
	v_pk_fma_f32 v[2:3], v[66:67], s[88:89], v[2:3] op_sel_hi:[1,0,1]
	v_pk_fma_f32 v[0:1], v[64:65], s[88:89], v[0:1] op_sel_hi:[1,0,1]
	global_store_dwordx4 v[32:33], v[28:31], off
	global_store_dwordx4 v[32:33], v[24:27], off offset:64
	global_store_dwordx4 v[32:33], v[20:23], off offset:512
	global_store_dwordx4 v[16:17], v[12:15], off
	global_store_dwordx4 v[16:17], v[8:11], off offset:64
	global_store_dwordx4 v[16:17], v[4:7], off offset:512
	global_store_dwordx4 v[16:17], v[0:3], off offset:576
